# v54 + ple-phase epilogue: within each 16-row group the three later (pp, x) load pairs hipcc serialised behind the x stores are issued with the first pair into free VGPR slots (renamed consumers, count
# speedup vs baseline: 1.0086x; 1.0014x over previous
; DI void gemm8_accum(f32x4 (&acc)[8][4], const bf16_t* a, size_t lda, const bf16_t* b, size_t ldb, int nkb, bf16_t* L,
;                     const bool pre, const bf16_t* an, size_t ldan, const bf16_t* bn, size_t ldbn) {
;     ...
;   __syncthreads();
;   g8_store1(L + 32768, ra, lrow, lch);
;   g8_load1(ra, an, ldan, 0, lrow, lch);
;   __builtin_amdgcn_sched_barrier(0);
;   g8_compute<0, 1>(acc, L, wm, wn, lane);
;   __builtin_amdgcn_sched_barrier(0);
;   g8_store1(L + 32768 + 16384, rb, lrow, lch);
;   g8_load1(rb, bn, ldbn, 0, lrow, lch);
;   __builtin_amdgcn_sched_barrier(0);
.Lstg_1007_c:
	v_readlane_b32 s21, v254, 18
	s_add_i32 s6, s20, s21
	s_cmp_lt_u32 s6, 64
	s_cselect_b64 s[4:5], -1, 0
	s_and_b64 s[0:1], s[4:5], exec
	s_cselect_b32 s2, s6, s20
	s_lshl_b32 s0, s2, 1
	v_lshlrev_b32_e32 v226, 1, v190
	s_and_b32 s0, s0, 0x7fffffe0
	s_and_b32 s1, s2, 3
	v_add3_u32 v0, s7, v183, v226
	s_or_b32 s0, s1, s0
	v_readlane_b32 s26, v252, 25
	s_barrier
	s_waitcnt vmcnt(7)
	ds_write_b128 v0, v[34:37]
	s_waitcnt vmcnt(6)
	ds_write_b128 v0, v[42:45] offset:8192
	s_waitcnt vmcnt(5)
	ds_write_b128 v0, v[54:57] offset:16384
	s_waitcnt vmcnt(4)
	ds_write_b128 v0, v[94:97] offset:24576
	v_lshl_or_b32 v0, v189, 8, v184
	s_or_b32 s28, s0, s26
	s_lshl_b32 s2, s2, 15
	v_lshlrev_b64 v[218:219], 1, v[0:1]
	v_lshl_or_b32 v0, v188, 8, v184
	s_lshl_b64 s[0:1], s[28:29], 17
	s_and_b32 s20, s2, 0x60000
	v_lshlrev_b64 v[220:221], 1, v[0:1]
	v_lshl_or_b32 v0, v187, 8, v184
	s_add_u32 s2, s38, s0
	v_lshlrev_b64 v[222:223], 1, v[0:1]
	v_lshl_or_b32 v0, v185, 8, v184
	s_addc_u32 s3, s39, s1
	v_lshlrev_b64 v[224:225], 1, v[0:1]
	v_lshl_add_u64 v[34:35], s[2:3], 0, v[218:219]
	v_lshl_add_u64 v[42:43], s[2:3], 0, v[220:221]
	v_lshl_add_u64 v[54:55], s[2:3], 0, v[222:223]
	v_lshl_add_u64 v[94:95], s[2:3], 0, v[224:225]
	global_load_dwordx4 v[34:37], v[34:35], off
	v_readlane_b32 s24, v254, 47
	global_load_dwordx4 v[42:45], v[42:43], off
	v_readlane_b32 s25, v254, 48
	global_load_dwordx4 v[54:57], v[54:55], off
	s_add_u32 s0, s24, s20
	global_load_dwordx4 v[94:97], v[94:95], off
	s_addc_u32 s1, s25, 0
	v_lshlrev_b32_e32 v0, 1, v186
	v_add_u32_e32 v202, 0, v0
	v_add_u32_e32 v198, v202, v181
	ds_read_b128 v[164:167], v198
	ds_read_b128 v[168:171], v198 offset:2048
	ds_read_b128 v[172:175], v198 offset:4096
	ds_read_b128 v[176:179], v198 offset:6144
	ds_read_b128 v[184:187], v198 offset:8192
	ds_read_b128 v[188:191], v198 offset:10240
	ds_read_b128 v[192:195], v198 offset:12288
	ds_read_b128 v[198:201], v198 offset:14336
	v_add_u32_e32 v214, v202, v180
	ds_read_b128 v[202:205], v214 offset:32768
	ds_read_b128 v[206:209], v214 offset:34816
	ds_read_b128 v[210:213], v214 offset:36864
	ds_read_b128 v[214:217], v214 offset:38912
	s_waitcnt lgkmcnt(3)
	v_mfma_f32_16x16x32_bf16 v[158:161], v[202:205], v[164:167], v[158:161]
	s_waitcnt lgkmcnt(2)
	v_mfma_f32_16x16x32_bf16 v[154:157], v[206:209], v[164:167], v[154:157]
	s_waitcnt lgkmcnt(1)
	v_mfma_f32_16x16x32_bf16 v[150:153], v[210:213], v[164:167], v[150:153]
	s_waitcnt lgkmcnt(0)
	v_mfma_f32_16x16x32_bf16 v[146:149], v[214:217], v[164:167], v[146:149]
	v_mfma_f32_16x16x32_bf16 v[142:145], v[202:205], v[168:171], v[142:145]
	v_mfma_f32_16x16x32_bf16 v[138:141], v[206:209], v[168:171], v[138:141]
	v_mfma_f32_16x16x32_bf16 v[134:137], v[210:213], v[168:171], v[134:137]
	v_mfma_f32_16x16x32_bf16 v[130:133], v[214:217], v[168:171], v[130:133]
	v_mfma_f32_16x16x32_bf16 v[126:129], v[202:205], v[172:175], v[126:129]
	v_mfma_f32_16x16x32_bf16 v[122:125], v[206:209], v[172:175], v[122:125]
	v_mfma_f32_16x16x32_bf16 v[118:121], v[210:213], v[172:175], v[118:121]
	v_mfma_f32_16x16x32_bf16 v[114:117], v[214:217], v[172:175], v[114:117]
	v_mfma_f32_16x16x32_bf16 v[110:113], v[202:205], v[176:179], v[110:113]
	v_mfma_f32_16x16x32_bf16 v[106:109], v[206:209], v[176:179], v[106:109]
	v_mfma_f32_16x16x32_bf16 v[102:105], v[210:213], v[176:179], v[102:105]
	v_mfma_f32_16x16x32_bf16 v[98:101], v[214:217], v[176:179], v[98:101]
	v_mfma_f32_16x16x32_bf16 v[90:93], v[202:205], v[184:187], v[90:93]
	v_mfma_f32_16x16x32_bf16 v[86:89], v[206:209], v[184:187], v[86:89]
	v_mfma_f32_16x16x32_bf16 v[82:85], v[210:213], v[184:187], v[82:85]
	v_mfma_f32_16x16x32_bf16 v[78:81], v[214:217], v[184:187], v[78:81]
	v_mfma_f32_16x16x32_bf16 v[74:77], v[202:205], v[188:191], v[74:77]
	v_mfma_f32_16x16x32_bf16 v[70:73], v[206:209], v[188:191], v[70:73]
	v_mfma_f32_16x16x32_bf16 v[66:69], v[210:213], v[188:191], v[66:69]
	v_mfma_f32_16x16x32_bf16 v[62:65], v[214:217], v[188:191], v[62:65]
	v_mfma_f32_16x16x32_bf16 v[58:61], v[202:205], v[192:195], v[58:61]
	v_mfma_f32_16x16x32_bf16 v[50:53], v[206:209], v[192:195], v[50:53]
	v_mfma_f32_16x16x32_bf16 v[46:49], v[210:213], v[192:195], v[46:49]
	v_mfma_f32_16x16x32_bf16 v[38:41], v[214:217], v[192:195], v[38:41]
	v_mfma_f32_16x16x32_bf16 v[30:33], v[202:205], v[198:201], v[30:33]
	v_mfma_f32_16x16x32_bf16 v[26:29], v[206:209], v[198:201], v[26:29]
	v_mfma_f32_16x16x32_bf16 v[22:25], v[210:213], v[198:201], v[22:25]
	v_mfma_f32_16x16x32_bf16 v[18:21], v[214:217], v[198:201], v[18:21]
	v_readlane_b32 s2, v254, 36
	s_nop 1
	v_add3_u32 v164, s2, v183, v226
	s_waitcnt vmcnt(7)
	ds_write_b128 v164, v[14:17]
	s_waitcnt vmcnt(6)
	ds_write_b128 v164, v[2:5] offset:8192
	s_waitcnt vmcnt(5)
	ds_write_b128 v164, v[6:9] offset:16384
	s_waitcnt vmcnt(4)
	ds_write_b128 v164, v[10:13] offset:24576
	v_lshl_add_u64 v[2:3], s[0:1], 0, v[218:219]
	v_lshl_add_u64 v[6:7], s[0:1], 0, v[220:221]
	v_lshl_add_u64 v[10:11], s[0:1], 0, v[222:223]
	v_lshl_add_u64 v[14:15], s[0:1], 0, v[224:225]
	global_load_dwordx4 v[2:5], v[2:3], off
	s_nop 0
	global_load_dwordx4 v[6:9], v[6:7], off
	s_nop 0
	global_load_dwordx4 v[10:13], v[10:11], off
	s_nop 0
	global_load_dwordx4 v[14:17], v[14:15], off
	v_lshlrev_b32_e32 v194, 1, v182
	v_add_u32_e32 v195, 0, v194
	v_add_u32_e32 v198, v195, v181
	ds_read_b128 v[164:167], v198
	ds_read_b128 v[168:171], v198 offset:2048
	ds_read_b128 v[172:175], v198 offset:4096
	ds_read_b128 v[176:179], v198 offset:6144
	ds_read_b128 v[182:185], v198 offset:8192
	ds_read_b128 v[186:189], v198 offset:10240
	ds_read_b128 v[190:193], v198 offset:12288
	ds_read_b128 v[198:201], v198 offset:14336
	v_add_u32_e32 v195, v195, v180
	ds_read_b128 v[202:205], v195 offset:32768
	ds_read_b128 v[206:209], v195 offset:34816
	ds_read_b128 v[210:213], v195 offset:36864
	ds_read_b128 v[214:217], v195 offset:38912
	s_waitcnt lgkmcnt(3)
; DI void gemm8_accum(f32x4 (&acc)[8][4], const bf16_t* a, size_t lda, const bf16_t* b, size_t ldb, int nkb, bf16_t* L,
;                     const bool pre, const bf16_t* an, size_t ldan, const bf16_t* bn, size_t ldbn) {
;     ...
;   g8_compute<1, 2>(acc, L, wm, wn, lane);
;   __syncthreads();
;   g8_store1(L, ra, lrow, lch);
;   __builtin_amdgcn_sched_barrier(0);
;   g8_compute<0, 1>(acc, L + 32768, wm, wn, lane);
;   __builtin_amdgcn_sched_barrier(0);
;   g8_store1(L + 16384, rb, lrow, lch);
	v_mfma_f32_16x16x32_bf16 v[158:161], v[202:205], v[164:167], v[158:161]
	s_waitcnt lgkmcnt(2)
	v_mfma_f32_16x16x32_bf16 v[154:157], v[206:209], v[164:167], v[154:157]
	s_waitcnt lgkmcnt(1)
	v_mfma_f32_16x16x32_bf16 v[150:153], v[210:213], v[164:167], v[150:153]
	s_waitcnt lgkmcnt(0)
	v_mfma_f32_16x16x32_bf16 v[146:149], v[214:217], v[164:167], v[146:149]
	v_mfma_f32_16x16x32_bf16 v[142:145], v[202:205], v[168:171], v[142:145]
	v_mfma_f32_16x16x32_bf16 v[138:141], v[206:209], v[168:171], v[138:141]
	v_mfma_f32_16x16x32_bf16 v[134:137], v[210:213], v[168:171], v[134:137]
	v_mfma_f32_16x16x32_bf16 v[130:133], v[214:217], v[168:171], v[130:133]
	v_mfma_f32_16x16x32_bf16 v[126:129], v[202:205], v[172:175], v[126:129]
	v_mfma_f32_16x16x32_bf16 v[122:125], v[206:209], v[172:175], v[122:125]
	v_mfma_f32_16x16x32_bf16 v[118:121], v[210:213], v[172:175], v[118:121]
	v_mfma_f32_16x16x32_bf16 v[114:117], v[214:217], v[172:175], v[114:117]
	v_mfma_f32_16x16x32_bf16 v[110:113], v[202:205], v[176:179], v[110:113]
	v_mfma_f32_16x16x32_bf16 v[106:109], v[206:209], v[176:179], v[106:109]
	v_mfma_f32_16x16x32_bf16 v[102:105], v[210:213], v[176:179], v[102:105]
	v_mfma_f32_16x16x32_bf16 v[98:101], v[214:217], v[176:179], v[98:101]
	v_mfma_f32_16x16x32_bf16 v[90:93], v[202:205], v[182:185], v[90:93]
	v_mfma_f32_16x16x32_bf16 v[86:89], v[206:209], v[182:185], v[86:89]
	v_mfma_f32_16x16x32_bf16 v[82:85], v[210:213], v[182:185], v[82:85]
	v_mfma_f32_16x16x32_bf16 v[78:81], v[214:217], v[182:185], v[78:81]
	v_mfma_f32_16x16x32_bf16 v[74:77], v[202:205], v[186:189], v[74:77]
	v_mfma_f32_16x16x32_bf16 v[70:73], v[206:209], v[186:189], v[70:73]
	v_mfma_f32_16x16x32_bf16 v[66:69], v[210:213], v[186:189], v[66:69]
	v_mfma_f32_16x16x32_bf16 v[62:65], v[214:217], v[186:189], v[62:65]
	v_mfma_f32_16x16x32_bf16 v[58:61], v[202:205], v[190:193], v[58:61]
	v_mfma_f32_16x16x32_bf16 v[50:53], v[206:209], v[190:193], v[50:53]
	v_mfma_f32_16x16x32_bf16 v[46:49], v[210:213], v[190:193], v[46:49]
	v_mfma_f32_16x16x32_bf16 v[38:41], v[214:217], v[190:193], v[38:41]
	v_mfma_f32_16x16x32_bf16 v[30:33], v[202:205], v[198:201], v[30:33]
	v_mfma_f32_16x16x32_bf16 v[26:29], v[206:209], v[198:201], v[26:29]
	v_mfma_f32_16x16x32_bf16 v[22:25], v[210:213], v[198:201], v[22:25]
	v_mfma_f32_16x16x32_bf16 v[18:21], v[214:217], v[198:201], v[18:21]
	s_barrier
	s_waitcnt vmcnt(7)
	ds_write_b128 v163, v[34:37]
	s_waitcnt vmcnt(6)
	ds_write_b128 v163, v[42:45] offset:8192
	s_waitcnt vmcnt(5)
	ds_write_b128 v163, v[54:57] offset:16384
	s_waitcnt vmcnt(4)
	ds_write_b128 v163, v[94:97] offset:24576
	v_add3_u32 v176, s7, v0, v181
	ds_read_b128 v[34:37], v176
	ds_read_b128 v[42:45], v176 offset:2048
	ds_read_b128 v[54:57], v176 offset:4096
	ds_read_b128 v[94:97], v176 offset:6144
	ds_read_b128 v[164:167], v176 offset:8192
	ds_read_b128 v[168:171], v176 offset:10240
	ds_read_b128 v[172:175], v176 offset:12288
	ds_read_b128 v[176:179], v176 offset:14336
	v_add3_u32 v0, s2, v0, v180
	ds_read_b128 v[182:185], v0
	ds_read_b128 v[186:189], v0 offset:2048
	ds_read_b128 v[190:193], v0 offset:4096
	ds_read_b128 v[198:201], v0 offset:6144
	s_waitcnt lgkmcnt(3)
	v_mfma_f32_16x16x32_bf16 v[158:161], v[182:185], v[34:37], v[158:161]
	s_waitcnt lgkmcnt(2)
	v_mfma_f32_16x16x32_bf16 v[154:157], v[186:189], v[34:37], v[154:157]
	s_waitcnt lgkmcnt(1)
	v_mfma_f32_16x16x32_bf16 v[150:153], v[190:193], v[34:37], v[150:153]
	s_waitcnt lgkmcnt(0)
	v_mfma_f32_16x16x32_bf16 v[34:37], v[198:201], v[34:37], v[146:149]
	v_mfma_f32_16x16x32_bf16 v[142:145], v[182:185], v[42:45], v[142:145]
	v_mfma_f32_16x16x32_bf16 v[138:141], v[186:189], v[42:45], v[138:141]
	v_mfma_f32_16x16x32_bf16 v[134:137], v[190:193], v[42:45], v[134:137]
	v_mfma_f32_16x16x32_bf16 v[42:45], v[198:201], v[42:45], v[130:133]
	v_mfma_f32_16x16x32_bf16 v[130:133], v[182:185], v[54:57], v[126:129]
	v_mfma_f32_16x16x32_bf16 v[146:149], v[186:189], v[54:57], v[122:125]
	v_mfma_f32_16x16x32_bf16 v[202:205], v[190:193], v[54:57], v[118:121]
	v_mfma_f32_16x16x32_bf16 v[54:57], v[198:201], v[54:57], v[114:117]
	v_mfma_f32_16x16x32_bf16 v[206:209], v[182:185], v[94:97], v[110:113]
	v_mfma_f32_16x16x32_bf16 v[210:213], v[186:189], v[94:97], v[106:109]
	v_mfma_f32_16x16x32_bf16 v[214:217], v[190:193], v[94:97], v[102:105]
	v_mfma_f32_16x16x32_bf16 v[218:221], v[198:201], v[94:97], v[98:101]
	v_mfma_f32_16x16x32_bf16 v[222:225], v[182:185], v[164:167], v[90:93]
	v_mfma_f32_16x16x32_bf16 v[226:229], v[186:189], v[164:167], v[86:89]
	v_mfma_f32_16x16x32_bf16 v[230:233], v[190:193], v[164:167], v[82:85]
	v_mfma_f32_16x16x32_bf16 v[164:167], v[198:201], v[164:167], v[78:81]
	v_mfma_f32_16x16x32_bf16 v[234:237], v[182:185], v[168:171], v[74:77]
	v_mfma_f32_16x16x32_bf16 v[238:241], v[186:189], v[168:171], v[70:73]
	v_mfma_f32_16x16x32_bf16 v[242:245], v[190:193], v[168:171], v[66:69]
	v_mfma_f32_16x16x32_bf16 v[168:171], v[198:201], v[168:171], v[62:65]
	v_mfma_f32_16x16x32_bf16 v[246:249], v[182:185], v[172:175], v[58:61]
	v_mfma_f32_16x16x32_bf16 v[50:53], v[186:189], v[172:175], v[50:53]
	v_mfma_f32_16x16x32_bf16 v[46:49], v[190:193], v[172:175], v[46:49]
	v_mfma_f32_16x16x32_bf16 v[172:175], v[198:201], v[172:175], v[38:41]
	v_mfma_f32_16x16x32_bf16 v[182:185], v[182:185], v[176:179], v[30:33]
	v_mfma_f32_16x16x32_bf16 v[186:189], v[186:189], v[176:179], v[26:29]
	v_mfma_f32_16x16x32_bf16 v[190:193], v[190:193], v[176:179], v[22:25]
	v_mfma_f32_16x16x32_bf16 v[176:179], v[198:201], v[176:179], v[18:21]
	s_waitcnt vmcnt(3)
	ds_write_b128 v163, v[2:5] offset:32768
	s_waitcnt vmcnt(2)
	ds_write_b128 v163, v[6:9] offset:40960
	s_waitcnt vmcnt(1)
; DI int TID8() { int t = threadIdx.x; asm volatile("" : "+v"(t)); return t; }
; DI void gemm8_accum(f32x4 (&acc)[8][4], const bf16_t* a, size_t lda, const bf16_t* b, size_t ldb, int nkb, bf16_t* L,
;                     const bool pre, const bf16_t* an, size_t ldan, const bf16_t* bn, size_t ldbn) {
;     ...
;   g8_store1(L + 16384, rb, lrow, lch);
;   __builtin_amdgcn_sched_barrier(0);
;   g8_compute<1, 2>(acc, L + 32768, wm, wn, lane);
;   __syncthreads();
; DI void row_rs8(float (&rsv)[8], const float* rowpart, int m0) {
;   const int tid = TID8(), lane = tid & 63, wm = tid >> 8;
; #pragma unroll
;   for (int i = 0; i < 8; ++i) {
;     const int m = m0 + wm * 128 + i * 16 + (lane & 15);
;     float s = 0.f;
; #pragma unroll
;     for (int t = 0; t < 8; ++t) s += rowpart[(size_t)t * T_TOK + m];
;     rsv[i] = rsqrtf(s * (1.f / 1024.f) + 1e-6f);
;   }
; }
	ds_write_b128 v163, v[10:13] offset:49152
	s_waitcnt vmcnt(0)
	ds_write_b128 v163, v[14:17] offset:57344
	v_add3_u32 v0, s7, v194, v181
	ds_read_b128 v[2:5], v0
	ds_read_b128 v[6:9], v0 offset:2048
	ds_read_b128 v[10:13], v0 offset:4096
	ds_read_b128 v[14:17], v0 offset:6144
	ds_read_b128 v[18:21], v0 offset:8192
	ds_read_b128 v[22:25], v0 offset:10240
	ds_read_b128 v[198:201], v0 offset:12288
	ds_read_b128 v[26:29], v0 offset:14336
	v_add3_u32 v0, s2, v194, v180
	ds_read_b128 v[30:33], v0
	ds_read_b128 v[38:41], v0 offset:2048
	ds_read_b128 v[58:61], v0 offset:4096
	ds_read_b128 v[62:65], v0 offset:6144
	s_waitcnt lgkmcnt(3)
	v_mfma_f32_16x16x32_bf16 v[126:129], v[30:33], v[2:5], v[158:161]
	s_waitcnt lgkmcnt(2)
	v_mfma_f32_16x16x32_bf16 v[122:125], v[38:41], v[2:5], v[154:157]
	s_waitcnt lgkmcnt(1)
	v_mfma_f32_16x16x32_bf16 v[118:121], v[58:61], v[2:5], v[150:153]
	s_waitcnt lgkmcnt(0)
	v_mfma_f32_16x16x32_bf16 v[114:117], v[62:65], v[2:5], v[34:37]
	v_mfma_f32_16x16x32_bf16 v[110:113], v[30:33], v[6:9], v[142:145]
	v_mfma_f32_16x16x32_bf16 v[106:109], v[38:41], v[6:9], v[138:141]
	v_mfma_f32_16x16x32_bf16 v[102:105], v[58:61], v[6:9], v[134:137]
	v_mfma_f32_16x16x32_bf16 v[98:101], v[62:65], v[6:9], v[42:45]
	v_mfma_f32_16x16x32_bf16 v[94:97], v[30:33], v[10:13], v[130:133]
	v_mfma_f32_16x16x32_bf16 v[90:93], v[38:41], v[10:13], v[146:149]
	v_mfma_f32_16x16x32_bf16 v[86:89], v[58:61], v[10:13], v[202:205]
	v_mfma_f32_16x16x32_bf16 v[82:85], v[62:65], v[10:13], v[54:57]
	v_mfma_f32_16x16x32_bf16 v[78:81], v[30:33], v[14:17], v[206:209]
	v_mfma_f32_16x16x32_bf16 v[74:77], v[38:41], v[14:17], v[210:213]
	v_mfma_f32_16x16x32_bf16 v[70:73], v[58:61], v[14:17], v[214:217]
	v_mfma_f32_16x16x32_bf16 v[66:69], v[62:65], v[14:17], v[218:221]
	v_mfma_f32_16x16x32_bf16 v[214:217], v[30:33], v[18:21], v[222:225]
	v_mfma_f32_16x16x32_bf16 v[210:213], v[38:41], v[18:21], v[226:229]
	v_mfma_f32_16x16x32_bf16 v[54:57], v[58:61], v[18:21], v[230:233]
	v_mfma_f32_16x16x32_bf16 v[158:161], v[62:65], v[18:21], v[164:167]
	v_mfma_f32_16x16x32_bf16 v[164:167], v[30:33], v[22:25], v[234:237]
	v_mfma_f32_16x16x32_bf16 v[42:45], v[38:41], v[22:25], v[238:241]
	v_mfma_f32_16x16x32_bf16 v[206:209], v[58:61], v[22:25], v[242:245]
	v_mfma_f32_16x16x32_bf16 v[34:37], v[62:65], v[22:25], v[168:171]
	v_mfma_f32_16x16x32_bf16 v[202:205], v[30:33], v[198:201], v[246:249]
	v_mfma_f32_16x16x32_bf16 v[168:171], v[38:41], v[198:201], v[50:53]
	v_mfma_f32_16x16x32_bf16 v[22:25], v[58:61], v[198:201], v[46:49]
	v_mfma_f32_16x16x32_bf16 v[18:21], v[62:65], v[198:201], v[172:175]
	v_mfma_f32_16x16x32_bf16 v[14:17], v[30:33], v[26:29], v[182:185]
	v_mfma_f32_16x16x32_bf16 v[10:13], v[38:41], v[26:29], v[186:189]
	v_mfma_f32_16x16x32_bf16 v[6:9], v[58:61], v[26:29], v[190:193]
	v_mfma_f32_16x16x32_bf16 v[2:5], v[62:65], v[26:29], v[176:179]
	v_mov_b32_e32 v0, v196
	s_barrier
	v_readlane_b32 s0, v251, 51
	v_ashrrev_i32_e32 v26, 1, v0
	v_and_b32_e32 v26, 0xffffff80, v26
	v_and_or_b32 v0, v0, 15, s13
	v_add_u32_e32 v26, v0, v26
	v_ashrrev_i32_e32 v27, 31, v26
	v_readlane_b32 s1, v251, 52
	s_mov_b32 s20, 0x3a800000
	s_mov_b32 s28, 0x45800000
	v_lshl_add_u64 v[148:149], v[26:27], 2, s[0:1]
	s_mov_b32 s0, 0x20000
	v_add_co_u32_e32 v146, vcc, s0, v148
	s_mov_b32 s0, 0x40000
	s_nop 0
	v_addc_co_u32_e32 v147, vcc, 0, v149, vcc
	v_add_co_u32_e32 v144, vcc, s0, v148
	s_mov_b32 s0, 0x60000
	s_nop 0
	v_addc_co_u32_e32 v145, vcc, 0, v149, vcc
	v_add_co_u32_e32 v142, vcc, s0, v148
	s_mov_b32 s0, 0x80000
	s_nop 0
	v_addc_co_u32_e32 v143, vcc, 0, v149, vcc
	v_add_co_u32_e32 v136, vcc, s0, v148
	s_mov_b32 s0, 0xa0000
	s_nop 0
	v_addc_co_u32_e32 v137, vcc, 0, v149, vcc
	v_add_co_u32_e32 v134, vcc, s0, v148
	s_mov_b32 s0, 0xc0000
	s_nop 0
	v_addc_co_u32_e32 v135, vcc, 0, v149, vcc
	v_add_co_u32_e32 v132, vcc, s0, v148
	s_mov_b32 s0, 0xe0000
	s_nop 0
	v_addc_co_u32_e32 v133, vcc, 0, v149, vcc
	v_add_co_u32_e32 v130, vcc, s0, v148
	global_load_dword v26, v[148:149], off
	global_load_dword v28, v[146:147], off
	global_load_dword v30, v[144:145], off
	global_load_dword v32, v[142:143], off
	global_load_dword v38, v[136:137], off
	global_load_dword v40, v[134:135], off
	global_load_dword v46, v[132:133], off
	v_addc_co_u32_e32 v131, vcc, 0, v149, vcc
	global_load_dword v48, v[130:131], off
	global_load_dword v27, v[148:149], off offset:64
	global_load_dword v29, v[146:147], off offset:64
	global_load_dword v31, v[144:145], off offset:64
	global_load_dword v33, v[142:143], off offset:64
	global_load_dword v39, v[136:137], off offset:64
	global_load_dword v41, v[134:135], off offset:64
	global_load_dword v47, v[132:133], off offset:64
	global_load_dword v49, v[130:131], off offset:64
	s_mov_b32 s0, 0x358637bd
	v_mov_b64_e32 v[140:141], s[0:1]
	s_mov_b32 s0, 0x800000
	s_add_i32 s9, s9, s21
	s_waitcnt vmcnt(7)
	v_pk_add_f32 v[26:27], v[26:27], 0 op_sel_hi:[1,0]
	s_waitcnt vmcnt(6)
	v_pk_add_f32 v[26:27], v[26:27], v[28:29]
	s_waitcnt vmcnt(5)
	v_pk_add_f32 v[26:27], v[26:27], v[30:31]
	s_waitcnt vmcnt(4)
	v_pk_add_f32 v[26:27], v[26:27], v[32:33]
	s_waitcnt vmcnt(3)
	v_pk_add_f32 v[26:27], v[26:27], v[38:39]
	s_waitcnt vmcnt(2)
	v_pk_add_f32 v[26:27], v[26:27], v[40:41]
	s_waitcnt vmcnt(1)
	v_pk_add_f32 v[26:27], v[26:27], v[46:47]
	s_waitcnt vmcnt(0)
; DI int TID8() { int t = threadIdx.x; asm volatile("" : "+v"(t)); return t; }
; DI void row_rs8(float (&rsv)[8], const float* rowpart, int m0) {
;   const int tid = TID8(), lane = tid & 63, wm = tid >> 8;
; #pragma unroll
;   for (int i = 0; i < 8; ++i) {
;     const int m = m0 + wm * 128 + i * 16 + (lane & 15);
;     float s = 0.f;
; #pragma unroll
;     for (int t = 0; t < 8; ++t) s += rowpart[(size_t)t * T_TOK + m];
;     rsv[i] = rsqrtf(s * (1.f / 1024.f) + 1e-6f);
;   }
; }
; DI void scale_rows8(f32x4 (&acc)[8][4], const float (&rsv)[8]) {
; #pragma unroll
;   for (int i = 0; i < 8; ++i)
; #pragma unroll
;     for (int j = 0; j < 4; ++j) acc[i][j] *= rsv[i];
; }
	v_pk_add_f32 v[26:27], v[26:27], v[48:49]
	s_nop 0
	v_pk_fma_f32 v[26:27], v[26:27], s[20:21], v[140:141] op_sel_hi:[1,0,0]
	s_nop 0
	v_mul_f32_e32 v0, 0x4b800000, v26
	v_cmp_gt_f32_e64 s[2:3], s0, v26
	v_cmp_gt_f32_e32 vcc, s0, v27
	s_nop 0
	v_cndmask_b32_e64 v0, v26, v0, s[2:3]
	v_rsq_f32_e32 v26, v0
	v_mul_f32_e32 v0, 0x4b800000, v27
	v_cndmask_b32_e32 v0, v27, v0, vcc
	v_rsq_f32_e32 v27, v0
	s_nop 0
	v_pk_mul_f32 v[28:29], v[26:27], s[28:29] op_sel_hi:[1,0]
	s_nop 0
	v_cndmask_b32_e32 v0, v27, v29, vcc
	v_cndmask_b32_e64 v138, v26, v28, s[2:3]
	global_load_dword v26, v[148:149], off offset:128
	global_load_dword v28, v[146:147], off offset:128
	global_load_dword v30, v[144:145], off offset:128
	global_load_dword v32, v[142:143], off offset:128
	global_load_dword v38, v[136:137], off offset:128
	global_load_dword v40, v[134:135], off offset:128
	global_load_dword v46, v[132:133], off offset:128
	global_load_dword v48, v[130:131], off offset:128
	global_load_dword v27, v[148:149], off offset:192
	global_load_dword v29, v[146:147], off offset:192
	global_load_dword v31, v[144:145], off offset:192
	global_load_dword v33, v[142:143], off offset:192
	global_load_dword v39, v[136:137], off offset:192
	global_load_dword v41, v[134:135], off offset:192
	global_load_dword v47, v[132:133], off offset:192
	global_load_dword v49, v[130:131], off offset:192
	s_waitcnt vmcnt(7)
	v_pk_add_f32 v[26:27], v[26:27], 0 op_sel_hi:[1,0]
	s_waitcnt vmcnt(6)
	v_pk_add_f32 v[26:27], v[26:27], v[28:29]
	s_waitcnt vmcnt(5)
	v_pk_add_f32 v[26:27], v[26:27], v[30:31]
	s_waitcnt vmcnt(4)
	v_pk_add_f32 v[26:27], v[26:27], v[32:33]
	s_waitcnt vmcnt(3)
	v_pk_add_f32 v[26:27], v[26:27], v[38:39]
	s_waitcnt vmcnt(2)
	v_pk_add_f32 v[26:27], v[26:27], v[40:41]
	s_waitcnt vmcnt(1)
	v_pk_add_f32 v[26:27], v[26:27], v[46:47]
	s_waitcnt vmcnt(0)
	v_pk_add_f32 v[26:27], v[26:27], v[48:49]
	s_nop 0
	v_pk_fma_f32 v[26:27], v[26:27], s[20:21], v[140:141] op_sel_hi:[1,0,0]
	s_nop 0
	v_mul_f32_e32 v28, 0x4b800000, v26
	v_cmp_gt_f32_e64 s[2:3], s0, v26
	v_cmp_gt_f32_e32 vcc, s0, v27
	s_nop 0
	v_cndmask_b32_e64 v26, v26, v28, s[2:3]
	v_mul_f32_e32 v28, 0x4b800000, v27
	v_cndmask_b32_e32 v27, v27, v28, vcc
	v_rsq_f32_e32 v26, v26
	v_rsq_f32_e32 v27, v27
	s_nop 0
	v_pk_mul_f32 v[28:29], v[26:27], s[28:29] op_sel_hi:[1,0]
	s_nop 0
	v_cndmask_b32_e32 v150, v27, v29, vcc
	v_cndmask_b32_e64 v152, v26, v28, s[2:3]
	global_load_dword v26, v[148:149], off offset:256
	global_load_dword v28, v[146:147], off offset:256
	global_load_dword v30, v[144:145], off offset:256
	global_load_dword v32, v[142:143], off offset:256
	global_load_dword v38, v[136:137], off offset:256
	global_load_dword v40, v[134:135], off offset:256
	global_load_dword v46, v[132:133], off offset:256
	global_load_dword v48, v[130:131], off offset:256
	global_load_dword v27, v[148:149], off offset:320
	global_load_dword v29, v[146:147], off offset:320
	global_load_dword v31, v[144:145], off offset:320
	global_load_dword v33, v[142:143], off offset:320
	global_load_dword v39, v[136:137], off offset:320
	global_load_dword v41, v[134:135], off offset:320
	global_load_dword v47, v[132:133], off offset:320
	global_load_dword v49, v[130:131], off offset:320
	s_waitcnt vmcnt(7)
	v_pk_add_f32 v[26:27], v[26:27], 0 op_sel_hi:[1,0]
	s_waitcnt vmcnt(6)
	v_pk_add_f32 v[26:27], v[26:27], v[28:29]
	s_waitcnt vmcnt(5)
	v_pk_add_f32 v[26:27], v[26:27], v[30:31]
	s_waitcnt vmcnt(4)
	v_pk_add_f32 v[26:27], v[26:27], v[32:33]
	s_waitcnt vmcnt(3)
	v_pk_add_f32 v[26:27], v[26:27], v[38:39]
	s_waitcnt vmcnt(2)
	v_pk_add_f32 v[26:27], v[26:27], v[40:41]
	s_waitcnt vmcnt(1)
	v_pk_add_f32 v[26:27], v[26:27], v[46:47]
	s_waitcnt vmcnt(0)
	v_pk_add_f32 v[26:27], v[26:27], v[48:49]
	s_nop 0
	v_pk_fma_f32 v[26:27], v[26:27], s[20:21], v[140:141] op_sel_hi:[1,0,0]
	s_nop 0
	v_mul_f32_e32 v28, 0x4b800000, v26
	v_cmp_gt_f32_e64 s[2:3], s0, v26
	v_cmp_gt_f32_e32 vcc, s0, v27
	s_nop 0
	v_cndmask_b32_e64 v26, v26, v28, s[2:3]
	v_mul_f32_e32 v28, 0x4b800000, v27
	v_cndmask_b32_e32 v27, v27, v28, vcc
	v_rsq_f32_e32 v26, v26
	v_rsq_f32_e32 v27, v27
	s_nop 0
	v_pk_mul_f32 v[28:29], v[26:27], s[28:29] op_sel_hi:[1,0]
	s_nop 0
	v_cndmask_b32_e32 v154, v27, v29, vcc
	v_cndmask_b32_e64 v156, v26, v28, s[2:3]
	global_load_dword v26, v[148:149], off offset:384
	global_load_dword v28, v[146:147], off offset:384
	global_load_dword v30, v[144:145], off offset:384
	global_load_dword v32, v[142:143], off offset:384
	global_load_dword v38, v[136:137], off offset:384
	global_load_dword v40, v[134:135], off offset:384
	global_load_dword v46, v[132:133], off offset:384
	global_load_dword v48, v[130:131], off offset:384
	global_load_dword v27, v[148:149], off offset:448
	global_load_dword v29, v[146:147], off offset:448
	global_load_dword v31, v[144:145], off offset:448
	global_load_dword v33, v[142:143], off offset:448
	global_load_dword v39, v[136:137], off offset:448
	global_load_dword v41, v[134:135], off offset:448
	global_load_dword v47, v[132:133], off offset:448
	global_load_dword v49, v[130:131], off offset:448
	v_pk_mul_f32 v[134:135], v[128:129], v[138:139] op_sel_hi:[1,0]
	v_pk_mul_f32 v[128:129], v[124:125], v[138:139] op_sel_hi:[1,0]
	v_pk_mul_f32 v[132:133], v[122:123], v[138:139] op_sel_hi:[1,0]
	v_pk_mul_f32 v[122:123], v[120:121], v[138:139] op_sel_hi:[1,0]
	v_pk_mul_f32 v[124:125], v[118:119], v[138:139] op_sel_hi:[1,0]
	v_pk_mul_f32 v[118:119], v[116:117], v[138:139] op_sel_hi:[1,0]
	v_pk_mul_f32 v[120:121], v[114:115], v[138:139] op_sel_hi:[1,0]
	v_pk_mul_f32 v[114:115], v[112:113], v[0:1] op_sel_hi:[1,0]
	v_pk_mul_f32 v[116:117], v[110:111], v[0:1] op_sel_hi:[1,0]
; DI int TID8() { int t = threadIdx.x; asm volatile("" : "+v"(t)); return t; }
; DI void row_rs8(float (&rsv)[8], const float* rowpart, int m0) {
;   const int tid = TID8(), lane = tid & 63, wm = tid >> 8;
; #pragma unroll
;   for (int i = 0; i < 8; ++i) {
;     const int m = m0 + wm * 128 + i * 16 + (lane & 15);
;     float s = 0.f;
; #pragma unroll
;     for (int t = 0; t < 8; ++t) s += rowpart[(size_t)t * T_TOK + m];
;     rsv[i] = rsqrtf(s * (1.f / 1024.f) + 1e-6f);
;   }
; }
; DI void scale_rows8(f32x4 (&acc)[8][4], const float (&rsv)[8]) {
; #pragma unroll
;   for (int i = 0; i < 8; ++i)
; #pragma unroll
;     for (int j = 0; j < 4; ++j) acc[i][j] *= rsv[i];
; }
	v_pk_mul_f32 v[110:111], v[108:109], v[0:1] op_sel_hi:[1,0]
	v_pk_mul_f32 v[112:113], v[106:107], v[0:1] op_sel_hi:[1,0]
	v_pk_mul_f32 v[106:107], v[104:105], v[0:1] op_sel_hi:[1,0]
	v_pk_mul_f32 v[108:109], v[102:103], v[0:1] op_sel_hi:[1,0]
	v_pk_mul_f32 v[102:103], v[100:101], v[0:1] op_sel_hi:[1,0]
	v_pk_mul_f32 v[104:105], v[98:99], v[0:1] op_sel_hi:[1,0]
	v_mov_b32_e32 v0, v196
	v_pk_mul_f32 v[136:137], v[126:127], v[138:139] op_sel_hi:[1,0]
	v_pk_mul_f32 v[100:101], v[94:95], v[152:153] op_sel_hi:[1,0]
	v_pk_mul_f32 v[98:99], v[96:97], v[152:153] op_sel_hi:[1,0]
	v_pk_mul_f32 v[96:97], v[90:91], v[152:153] op_sel_hi:[1,0]
	v_pk_mul_f32 v[94:95], v[92:93], v[152:153] op_sel_hi:[1,0]
	v_pk_mul_f32 v[92:93], v[86:87], v[152:153] op_sel_hi:[1,0]
	v_pk_mul_f32 v[90:91], v[88:89], v[152:153] op_sel_hi:[1,0]
	v_pk_mul_f32 v[88:89], v[82:83], v[152:153] op_sel_hi:[1,0]
	v_pk_mul_f32 v[86:87], v[84:85], v[152:153] op_sel_hi:[1,0]
	v_pk_mul_f32 v[84:85], v[78:79], v[150:151] op_sel_hi:[1,0]
	v_pk_mul_f32 v[82:83], v[80:81], v[150:151] op_sel_hi:[1,0]
	v_pk_mul_f32 v[80:81], v[74:75], v[150:151] op_sel_hi:[1,0]
	v_pk_mul_f32 v[78:79], v[76:77], v[150:151] op_sel_hi:[1,0]
	v_pk_mul_f32 v[76:77], v[70:71], v[150:151] op_sel_hi:[1,0]
	v_pk_mul_f32 v[74:75], v[72:73], v[150:151] op_sel_hi:[1,0]
	v_pk_mul_f32 v[72:73], v[66:67], v[150:151] op_sel_hi:[1,0]
	v_pk_mul_f32 v[70:71], v[68:69], v[150:151] op_sel_hi:[1,0]
	v_pk_mul_f32 v[68:69], v[214:215], v[156:157] op_sel_hi:[1,0]
	v_pk_mul_f32 v[66:67], v[216:217], v[156:157] op_sel_hi:[1,0]
	v_pk_mul_f32 v[64:65], v[210:211], v[156:157] op_sel_hi:[1,0]
	v_pk_mul_f32 v[62:63], v[212:213], v[156:157] op_sel_hi:[1,0]
	v_pk_mul_f32 v[60:61], v[54:55], v[156:157] op_sel_hi:[1,0]
	v_pk_mul_f32 v[58:59], v[56:57], v[156:157] op_sel_hi:[1,0]
	v_pk_mul_f32 v[56:57], v[158:159], v[156:157] op_sel_hi:[1,0]
	v_pk_mul_f32 v[54:55], v[160:161], v[156:157] op_sel_hi:[1,0]
	v_pk_mul_f32 v[52:53], v[164:165], v[154:155] op_sel_hi:[1,0]
	v_pk_mul_f32 v[50:51], v[166:167], v[154:155] op_sel_hi:[1,0]
	s_waitcnt vmcnt(7)
	v_pk_add_f32 v[26:27], v[26:27], 0 op_sel_hi:[1,0]
	s_waitcnt vmcnt(6)
	v_pk_add_f32 v[26:27], v[26:27], v[28:29]
	s_waitcnt vmcnt(5)
	v_pk_add_f32 v[26:27], v[26:27], v[30:31]
	s_waitcnt vmcnt(4)
	v_pk_add_f32 v[26:27], v[26:27], v[32:33]
	s_waitcnt vmcnt(3)
	v_pk_add_f32 v[26:27], v[26:27], v[38:39]
	v_pk_mul_f32 v[38:39], v[36:37], v[154:155] op_sel_hi:[1,0]
	s_waitcnt vmcnt(2)
	v_pk_add_f32 v[26:27], v[26:27], v[40:41]
	v_pk_mul_f32 v[40:41], v[34:35], v[154:155] op_sel_hi:[1,0]
	s_waitcnt vmcnt(1)
	v_pk_add_f32 v[26:27], v[26:27], v[46:47]
	v_pk_mul_f32 v[46:47], v[44:45], v[154:155] op_sel_hi:[1,0]
	s_waitcnt vmcnt(0)
; DI float bflo(unsigned u) { return __uint_as_float(u << 16); }
; DI float bfhi(unsigned u) { return __uint_as_float(u & 0xffff0000u); }
; DI float sigmoidf(float x) { return __builtin_amdgcn_rcpf(1.f + __expf(-x)); }
; template <class E>
; DI void gemm8_epi(f32x4 (&acc)[8][4], int m0, int n0, E e) {
;     ...
; #pragma unroll
;   for (int i = 0; i < 8; ++i)
; #pragma unroll
;     for (int j = 0; j < 4; ++j) {
;       const int m = m0 + wm * 128 + i * 16 + (lane & 15);
;       const int n = n0 + wn * 64 + j * 16 + (lane >> 4) * 4;
;       e(m, n, acc[i][j]);
;     }
; __global__ void __launch_bounds__(512, 2) mega(Params p) {
;     ...
;       gemm8_epi(acc8, m0, n0, [&](int m, int n, f32x4& a) {
;         uint2 pv = *(const uint2*)(ppb + (size_t)m * DM + n);
;         float4* o = (float4*)(p.out + (size_t)m * DM + n);
;         float4 xv = *o;
;         *o = make_float4(xv.x + sigmoidf(a[0]) * bflo(pv.x), xv.y + sigmoidf(a[1]) * bfhi(pv.x),
;                          xv.z + sigmoidf(a[2]) * bflo(pv.y), xv.w + sigmoidf(a[3]) * bfhi(pv.y));
;       });
	v_pk_add_f32 v[26:27], v[26:27], v[48:49]
	v_pk_mul_f32 v[48:49], v[42:43], v[154:155] op_sel_hi:[1,0]
	v_pk_fma_f32 v[26:27], v[26:27], s[20:21], v[140:141] op_sel_hi:[1,0,0]
	v_pk_mul_f32 v[44:45], v[206:207], v[154:155] op_sel_hi:[1,0]
	v_mul_f32_e32 v28, 0x4b800000, v26
	v_cmp_gt_f32_e64 s[2:3], s0, v26
	v_cmp_gt_f32_e32 vcc, s0, v27
	v_pk_mul_f32 v[42:43], v[208:209], v[154:155] op_sel_hi:[1,0]
	v_cndmask_b32_e64 v26, v26, v28, s[2:3]
	v_mul_f32_e32 v28, 0x4b800000, v27
	v_cndmask_b32_e32 v27, v27, v28, vcc
	v_rsq_f32_e32 v26, v26
	v_rsq_f32_e32 v27, v27
	s_mov_b32 s20, s6
	v_pk_mul_f32 v[28:29], v[26:27], s[28:29] op_sel_hi:[1,0]
	s_nop 0
	v_cndmask_b32_e64 v28, v26, v28, s[2:3]
	v_cndmask_b32_e32 v130, v27, v29, vcc
	v_pk_mul_f32 v[26:27], v[22:23], v[28:29] op_sel_hi:[1,0]
	v_ashrrev_i32_e32 v23, 1, v0
	v_pk_mul_f32 v[34:35], v[204:205], v[28:29] op_sel_hi:[1,0]
	v_pk_mul_f32 v[36:37], v[202:203], v[28:29] op_sel_hi:[1,0]
	v_pk_mul_f32 v[30:31], v[170:171], v[28:29] op_sel_hi:[1,0]
	v_pk_mul_f32 v[32:33], v[168:169], v[28:29] op_sel_hi:[1,0]
	v_pk_mul_f32 v[24:25], v[24:25], v[28:29] op_sel_hi:[1,0]
	v_pk_mul_f32 v[20:21], v[20:21], v[28:29] op_sel_hi:[1,0]
	v_pk_mul_f32 v[18:19], v[18:19], v[28:29] op_sel_hi:[1,0]
	v_and_b32_e32 v22, 0xc0, v0
	v_and_b32_e32 v23, 0xffffff80, v23
	v_and_or_b32 v28, v0, 15, s13
	v_lshrrev_b32_e32 v0, 2, v0
	v_add_u32_e32 v28, v28, v23
	v_and_b32_e32 v0, 12, v0
	v_or3_b32 v140, v22, v0, s12
	v_ashrrev_i32_e32 v29, 31, v28
	v_readlane_b32 s12, v252, 47
	v_lshlrev_b64 v[22:23], 11, v[28:29]
	v_readlane_b32 s13, v252, 48
	v_lshlrev_b32_e32 v0, 1, v140
	v_pk_mul_f32 v[16:17], v[16:17], v[130:131] op_sel_hi:[1,0]
	v_lshl_add_u64 v[22:23], s[12:13], 0, v[22:23]
	v_pk_mul_f32 v[14:15], v[14:15], v[130:131] op_sel_hi:[1,0]
	v_pk_mul_f32 v[12:13], v[12:13], v[130:131] op_sel_hi:[1,0]
	v_pk_mul_f32 v[10:11], v[10:11], v[130:131] op_sel_hi:[1,0]
	v_pk_mul_f32 v[8:9], v[8:9], v[130:131] op_sel_hi:[1,0]
	v_pk_mul_f32 v[6:7], v[6:7], v[130:131] op_sel_hi:[1,0]
	v_pk_mul_f32 v[4:5], v[4:5], v[130:131] op_sel_hi:[1,0]
	v_pk_mul_f32 v[2:3], v[2:3], v[130:131] op_sel_hi:[1,0]
	v_lshl_add_u64 v[130:131], v[22:23], 0, v[0:1]
	v_lshlrev_b64 v[22:23], 12, v[28:29]
	v_mul_f32_e32 v29, 0xbfb8aa3b, v136
	v_exp_f32_e32 v29, v29
	v_readlane_b32 s0, v251, 33
	v_readlane_b32 s2, v251, 35
	v_readlane_b32 s3, v251, 36
	v_add_f32_e32 v29, 1.0, v29
	global_load_dwordx2 v[138:139], v[130:131], off
	v_lshl_add_u64 v[126:127], s[2:3], 0, v[22:23]
	v_lshlrev_b32_e32 v22, 2, v140
	v_rcp_f32_e32 v140, v29
	v_mul_f32_e32 v29, 0xbfb8aa3b, v137
	v_exp_f32_e32 v29, v29
	v_mov_b32_e32 v23, v1
	v_lshl_add_u64 v[126:127], v[126:127], 0, v[22:23]
	v_mul_f32_e32 v26, 0xbfb8aa3b, v26
	v_add_f32_e32 v29, 1.0, v29
	v_rcp_f32_e32 v141, v29
	v_mul_f32_e32 v29, 0xbfb8aa3b, v134
	v_exp_f32_e32 v29, v29
	v_mul_f32_e32 v24, 0xbfb8aa3b, v24
	v_exp_f32_e32 v26, v26
	v_exp_f32_e32 v24, v24
	v_add_f32_e32 v29, 1.0, v29
	v_rcp_f32_e32 v144, v29
	v_mul_f32_e32 v29, 0xbfb8aa3b, v135
	global_load_dwordx4 v[134:137], v[126:127], off
	global_load_dwordx2 v[146:147], v[130:131], off offset:32
	global_load_dwordx4 v[152:155], v[126:127], off offset:64
	global_load_dwordx2 v[148:149], v[130:131], off offset:64
	global_load_dwordx4 v[156:159], v[126:127], off offset:128
	global_load_dwordx2 v[150:151], v[130:131], off offset:96
	global_load_dwordx4 v[188:191], v[126:127], off offset:192
	v_exp_f32_e32 v29, v29
	v_add_f32_e32 v26, 1.0, v26
	v_add_f32_e32 v24, 1.0, v24
	v_mul_f32_e32 v18, 0xbfb8aa3b, v18
	v_add_f32_e32 v29, 1.0, v29
	v_rcp_f32_e32 v145, v29
	v_mul_f32_e32 v29, 0xbfb8aa3b, v132
	v_exp_f32_e32 v29, v29
	v_exp_f32_e32 v18, v18
	v_readlane_b32 s0, v254, 13
	v_readlane_b32 s1, v251, 34
	v_add_f32_e32 v29, 1.0, v29
	v_rcp_f32_e32 v132, v29
	v_mul_f32_e32 v29, 0xbfb8aa3b, v133
	v_exp_f32_e32 v29, v29
	v_add_f32_e32 v18, 1.0, v18
	s_add_i32 s11, s11, s0
	v_readlane_b32 s0, v254, 19
	v_add_f32_e32 v29, 1.0, v29
	v_rcp_f32_e32 v133, v29
	v_mul_f32_e32 v29, 0xbfb8aa3b, v128
	v_exp_f32_e32 v29, v29
	s_add_i32 s10, s10, s0
	s_mov_b64 s[0:1], -1
	s_and_b64 vcc, s[4:5], exec
	v_add_f32_e32 v29, 1.0, v29
	v_rcp_f32_e32 v128, v29
	v_mul_f32_e32 v29, 0xbfb8aa3b, v129
	v_exp_f32_e32 v29, v29
	s_waitcnt vmcnt(7)
	v_lshlrev_b32_e32 v142, 16, v138
	v_and_b32_e32 v143, 0xffff0000, v138
	v_lshlrev_b32_e32 v138, 16, v139
	v_and_b32_e32 v139, 0xffff0000, v139
	v_add_f32_e32 v29, 1.0, v29
	v_rcp_f32_e32 v129, v29
	v_mul_f32_e32 v29, 0xbfb8aa3b, v124
	v_exp_f32_e32 v29, v29
	s_waitcnt vmcnt(6)
	v_pk_fma_f32 v[134:135], v[140:141], v[142:143], v[134:135]
	v_pk_fma_f32 v[136:137], v[144:145], v[138:139], v[136:137]
	global_store_dwordx4 v[126:127], v[134:137], off

; DI float bflo(unsigned u) { return __uint_as_float(u << 16); }
; DI float bfhi(unsigned u) { return __uint_as_float(u & 0xffff0000u); }
; DI float sigmoidf(float x) { return __builtin_amdgcn_rcpf(1.f + __expf(-x)); }
; __global__ void __launch_bounds__(512, 2) mega(Params p) {
;     ...
;       gemm8_epi(acc8, m0, n0, [&](int m, int n, f32x4& a) {
;         uint2 pv = *(const uint2*)(ppb + (size_t)m * DM + n);
;         float4* o = (float4*)(p.out + (size_t)m * DM + n);
;         float4 xv = *o;
;         *o = make_float4(xv.x + sigmoidf(a[0]) * bflo(pv.x), xv.y + sigmoidf(a[1]) * bfhi(pv.x),
;                          xv.z + sigmoidf(a[2]) * bflo(pv.y), xv.w + sigmoidf(a[3]) * bfhi(pv.y));
;       });
	v_add_f32_e32 v29, 1.0, v29

; DI float bflo(unsigned u) { return __uint_as_float(u << 16); }
; DI float bfhi(unsigned u) { return __uint_as_float(u & 0xffff0000u); }
; DI float sigmoidf(float x) { return __builtin_amdgcn_rcpf(1.f + __expf(-x)); }
; __global__ void __launch_bounds__(512, 2) mega(Params p) {
;     ...
;       gemm8_epi(acc8, m0, n0, [&](int m, int n, f32x4& a) {
;         uint2 pv = *(const uint2*)(ppb + (size_t)m * DM + n);
;         float4* o = (float4*)(p.out + (size_t)m * DM + n);
;         float4 xv = *o;
;         *o = make_float4(xv.x + sigmoidf(a[0]) * bflo(pv.x), xv.y + sigmoidf(a[1]) * bfhi(pv.x),
;                          xv.z + sigmoidf(a[2]) * bflo(pv.y), xv.w + sigmoidf(a[3]) * bfhi(pv.y));
;       });
	s_waitcnt vmcnt(6)
	v_lshlrev_b32_e32 v134, 16, v146
	v_and_b32_e32 v135, 0xffff0000, v146
	v_lshlrev_b32_e32 v136, 16, v147
	v_and_b32_e32 v137, 0xffff0000, v147
	s_waitcnt vmcnt(5)
	v_pk_fma_f32 v[132:133], v[132:133], v[134:135], v[152:153]
	v_pk_fma_f32 v[134:135], v[128:129], v[136:137], v[154:155]
	global_store_dwordx4 v[126:127], v[132:135], off offset:64

; DI float bflo(unsigned u) { return __uint_as_float(u << 16); }
; DI float bfhi(unsigned u) { return __uint_as_float(u & 0xffff0000u); }
; DI float sigmoidf(float x) { return __builtin_amdgcn_rcpf(1.f + __expf(-x)); }
; __global__ void __launch_bounds__(512, 2) mega(Params p) {
;     ...
;       gemm8_epi(acc8, m0, n0, [&](int m, int n, f32x4& a) {
;         uint2 pv = *(const uint2*)(ppb + (size_t)m * DM + n);
;         float4* o = (float4*)(p.out + (size_t)m * DM + n);
;         float4 xv = *o;
;         *o = make_float4(xv.x + sigmoidf(a[0]) * bflo(pv.x), xv.y + sigmoidf(a[1]) * bfhi(pv.x),
;                          xv.z + sigmoidf(a[2]) * bflo(pv.y), xv.w + sigmoidf(a[3]) * bfhi(pv.y));
;       });
	s_nop 0
	v_rcp_f32_e32 v132, v29
	v_mul_f32_e32 v29, 0xbfb8aa3b, v125
	v_exp_f32_e32 v29, v29
	s_waitcnt vmcnt(5)
	v_lshlrev_b32_e32 v134, 16, v148
	v_add_f32_e32 v29, 1.0, v29
	v_rcp_f32_e32 v133, v29
	v_mul_f32_e32 v29, 0xbfb8aa3b, v122
	v_exp_f32_e32 v29, v29
	v_and_b32_e32 v135, 0xffff0000, v148
	v_lshlrev_b32_e32 v128, 16, v149
	v_and_b32_e32 v129, 0xffff0000, v149
	v_add_f32_e32 v29, 1.0, v29
	v_rcp_f32_e32 v136, v29
	v_mul_f32_e32 v29, 0xbfb8aa3b, v123

; DI float bflo(unsigned u) { return __uint_as_float(u << 16); }
; DI float bfhi(unsigned u) { return __uint_as_float(u & 0xffff0000u); }
; DI float sigmoidf(float x) { return __builtin_amdgcn_rcpf(1.f + __expf(-x)); }
; __global__ void __launch_bounds__(512, 2) mega(Params p) {
;     ...
;       gemm8_epi(acc8, m0, n0, [&](int m, int n, f32x4& a) {
;         uint2 pv = *(const uint2*)(ppb + (size_t)m * DM + n);
;         float4* o = (float4*)(p.out + (size_t)m * DM + n);
;         float4 xv = *o;
;         *o = make_float4(xv.x + sigmoidf(a[0]) * bflo(pv.x), xv.y + sigmoidf(a[1]) * bfhi(pv.x),
;                          xv.z + sigmoidf(a[2]) * bflo(pv.y), xv.w + sigmoidf(a[3]) * bfhi(pv.y));
;       });
	v_exp_f32_e32 v29, v29
	s_waitcnt vmcnt(4)
	v_pk_fma_f32 v[122:123], v[132:133], v[134:135], v[156:157]
	v_add_f32_e32 v29, 1.0, v29
	v_rcp_f32_e32 v137, v29
	v_mul_f32_e32 v29, 0xbfb8aa3b, v120
	v_exp_f32_e32 v29, v29
	v_pk_fma_f32 v[124:125], v[136:137], v[128:129], v[158:159]
	global_store_dwordx4 v[126:127], v[122:125], off offset:128
	v_add_f32_e32 v29, 1.0, v29

; DI float bflo(unsigned u) { return __uint_as_float(u << 16); }
; DI float bfhi(unsigned u) { return __uint_as_float(u & 0xffff0000u); }
; DI float sigmoidf(float x) { return __builtin_amdgcn_rcpf(1.f + __expf(-x)); }
; __global__ void __launch_bounds__(512, 2) mega(Params p) {
;     ...
;       gemm8_epi(acc8, m0, n0, [&](int m, int n, f32x4& a) {
;         uint2 pv = *(const uint2*)(ppb + (size_t)m * DM + n);
;         float4* o = (float4*)(p.out + (size_t)m * DM + n);
;         float4 xv = *o;
;         *o = make_float4(xv.x + sigmoidf(a[0]) * bflo(pv.x), xv.y + sigmoidf(a[1]) * bfhi(pv.x),
;                          xv.z + sigmoidf(a[2]) * bflo(pv.y), xv.w + sigmoidf(a[3]) * bfhi(pv.y));
;       });
	v_rcp_f32_e32 v124, v29
	v_mul_f32_e32 v29, 0xbfb8aa3b, v121
	v_exp_f32_e32 v29, v29
	s_waitcnt vmcnt(4)
	v_lshlrev_b32_e32 v128, 16, v150
	v_add_f32_e32 v29, 1.0, v29
	v_rcp_f32_e32 v125, v29
	v_mul_f32_e32 v29, 0xbfb8aa3b, v118
	v_exp_f32_e32 v29, v29
	v_and_b32_e32 v129, 0xffff0000, v150
	v_lshlrev_b32_e32 v122, 16, v151
	v_and_b32_e32 v123, 0xffff0000, v151
	v_add_f32_e32 v29, 1.0, v29
	v_rcp_f32_e32 v130, v29
	v_mul_f32_e32 v29, 0xbfb8aa3b, v119

; DI float bflo(unsigned u) { return __uint_as_float(u << 16); }
; DI float bfhi(unsigned u) { return __uint_as_float(u & 0xffff0000u); }
; DI float sigmoidf(float x) { return __builtin_amdgcn_rcpf(1.f + __expf(-x)); }
; template <class E>
; DI void gemm8_epi(f32x4 (&acc)[8][4], int m0, int n0, E e) {
;     ...
; #pragma unroll
;   for (int i = 0; i < 8; ++i)
; #pragma unroll
;     for (int j = 0; j < 4; ++j) {
;       const int m = m0 + wm * 128 + i * 16 + (lane & 15);
;       const int n = n0 + wn * 64 + j * 16 + (lane >> 4) * 4;
;       e(m, n, acc[i][j]);
;     }
; __global__ void __launch_bounds__(512, 2) mega(Params p) {
;     ...
;       gemm8_epi(acc8, m0, n0, [&](int m, int n, f32x4& a) {
;         uint2 pv = *(const uint2*)(ppb + (size_t)m * DM + n);
;         float4* o = (float4*)(p.out + (size_t)m * DM + n);
;         float4 xv = *o;
;         *o = make_float4(xv.x + sigmoidf(a[0]) * bflo(pv.x), xv.y + sigmoidf(a[1]) * bfhi(pv.x),
;                          xv.z + sigmoidf(a[2]) * bflo(pv.y), xv.w + sigmoidf(a[3]) * bfhi(pv.y));
;       });
	v_exp_f32_e32 v29, v29
	s_waitcnt vmcnt(3)
	v_pk_fma_f32 v[118:119], v[124:125], v[128:129], v[188:189]
	v_add_f32_e32 v29, 1.0, v29
	v_rcp_f32_e32 v131, v29
	v_mul_f32_e32 v29, 0xbfb8aa3b, v116
	v_exp_f32_e32 v29, v29
	v_pk_fma_f32 v[120:121], v[130:131], v[122:123], v[190:191]
	global_store_dwordx4 v[126:127], v[118:121], off offset:192
	v_add_f32_e32 v29, 1.0, v29
	v_rcp_f32_e32 v124, v29
	v_mul_f32_e32 v29, 0xbfb8aa3b, v117
	v_exp_f32_e32 v29, v29
	v_or_b32_e32 v118, 16, v28
	v_ashrrev_i32_e32 v119, 31, v118
	v_lshlrev_b64 v[120:121], 11, v[118:119]
	v_add_f32_e32 v29, 1.0, v29
	v_rcp_f32_e32 v125, v29
	v_mul_f32_e32 v29, 0xbfb8aa3b, v114
	v_exp_f32_e32 v29, v29
	v_lshl_add_u64 v[120:121], s[12:13], 0, v[120:121]
	v_lshlrev_b64 v[118:119], 12, v[118:119]
	v_lshl_add_u64 v[120:121], v[120:121], 0, v[0:1]
	v_lshl_add_u64 v[118:119], s[2:3], 0, v[118:119]
	global_load_dwordx2 v[122:123], v[120:121], off
	v_lshl_add_u64 v[118:119], v[118:119], 0, v[22:23]
	v_add_f32_e32 v29, 1.0, v29
	v_rcp_f32_e32 v128, v29
	v_mul_f32_e32 v29, 0xbfb8aa3b, v115
	global_load_dwordx4 v[114:117], v[118:119], off
	global_load_dwordx2 v[146:147], v[120:121], off offset:32
	global_load_dwordx4 v[152:155], v[118:119], off offset:64
	global_load_dwordx2 v[148:149], v[120:121], off offset:64
	global_load_dwordx4 v[156:159], v[118:119], off offset:128
	global_load_dwordx2 v[150:151], v[120:121], off offset:96
	global_load_dwordx4 v[188:191], v[118:119], off offset:192
	v_exp_f32_e32 v29, v29
	s_waitcnt vmcnt(7)
	v_lshlrev_b32_e32 v126, 16, v122
	v_add_f32_e32 v29, 1.0, v29
	v_rcp_f32_e32 v129, v29
	v_and_b32_e32 v127, 0xffff0000, v122
	v_lshlrev_b32_e32 v122, 16, v123
	v_and_b32_e32 v123, 0xffff0000, v123
	s_waitcnt vmcnt(6)
	v_pk_fma_f32 v[114:115], v[124:125], v[126:127], v[114:115]
	v_pk_fma_f32 v[116:117], v[128:129], v[122:123], v[116:117]
	global_store_dwordx4 v[118:119], v[114:117], off

; DI float bflo(unsigned u) { return __uint_as_float(u << 16); }
; DI float bfhi(unsigned u) { return __uint_as_float(u & 0xffff0000u); }
; DI float sigmoidf(float x) { return __builtin_amdgcn_rcpf(1.f + __expf(-x)); }
; __global__ void __launch_bounds__(512, 2) mega(Params p) {
;     ...
;       gemm8_epi(acc8, m0, n0, [&](int m, int n, f32x4& a) {
;         uint2 pv = *(const uint2*)(ppb + (size_t)m * DM + n);
;         float4* o = (float4*)(p.out + (size_t)m * DM + n);
;         float4 xv = *o;
;         *o = make_float4(xv.x + sigmoidf(a[0]) * bflo(pv.x), xv.y + sigmoidf(a[1]) * bfhi(pv.x),
;                          xv.z + sigmoidf(a[2]) * bflo(pv.y), xv.w + sigmoidf(a[3]) * bfhi(pv.y));
;       });
	v_mul_f32_e32 v29, 0xbfb8aa3b, v112

; DI float bflo(unsigned u) { return __uint_as_float(u << 16); }
; DI float bfhi(unsigned u) { return __uint_as_float(u & 0xffff0000u); }
; DI float sigmoidf(float x) { return __builtin_amdgcn_rcpf(1.f + __expf(-x)); }
; __global__ void __launch_bounds__(512, 2) mega(Params p) {
;     ...
;       gemm8_epi(acc8, m0, n0, [&](int m, int n, f32x4& a) {
;         uint2 pv = *(const uint2*)(ppb + (size_t)m * DM + n);
;         float4* o = (float4*)(p.out + (size_t)m * DM + n);
;         float4 xv = *o;
;         *o = make_float4(xv.x + sigmoidf(a[0]) * bflo(pv.x), xv.y + sigmoidf(a[1]) * bfhi(pv.x),
;                          xv.z + sigmoidf(a[2]) * bflo(pv.y), xv.w + sigmoidf(a[3]) * bfhi(pv.y));
;       });
	v_exp_f32_e32 v29, v29
	s_waitcnt vmcnt(6)
	v_lshlrev_b32_e32 v114, 16, v146
	v_add_f32_e32 v29, 1.0, v29
	v_rcp_f32_e32 v112, v29
	v_mul_f32_e32 v29, 0xbfb8aa3b, v113
	v_exp_f32_e32 v29, v29
	v_and_b32_e32 v115, 0xffff0000, v146
	v_lshlrev_b32_e32 v116, 16, v147
	v_and_b32_e32 v117, 0xffff0000, v147
	v_add_f32_e32 v29, 1.0, v29
	v_rcp_f32_e32 v113, v29
	v_mul_f32_e32 v29, 0xbfb8aa3b, v110
	v_exp_f32_e32 v29, v29
	s_waitcnt vmcnt(5)
	v_pk_fma_f32 v[112:113], v[112:113], v[114:115], v[152:153]
	v_add_f32_e32 v29, 1.0, v29
	v_rcp_f32_e32 v110, v29
	v_mul_f32_e32 v29, 0xbfb8aa3b, v111
	v_exp_f32_e32 v29, v29
	s_nop 0
	v_add_f32_e32 v29, 1.0, v29
	v_rcp_f32_e32 v111, v29
	v_mul_f32_e32 v29, 0xbfb8aa3b, v108
	v_exp_f32_e32 v29, v29
	v_pk_fma_f32 v[114:115], v[110:111], v[116:117], v[154:155]
	global_store_dwordx4 v[118:119], v[112:115], off offset:64
	v_add_f32_e32 v29, 1.0, v29

; DI float bflo(unsigned u) { return __uint_as_float(u << 16); }
; DI float bfhi(unsigned u) { return __uint_as_float(u & 0xffff0000u); }
; DI float sigmoidf(float x) { return __builtin_amdgcn_rcpf(1.f + __expf(-x)); }
; __global__ void __launch_bounds__(512, 2) mega(Params p) {
;     ...
;       gemm8_epi(acc8, m0, n0, [&](int m, int n, f32x4& a) {
;         uint2 pv = *(const uint2*)(ppb + (size_t)m * DM + n);
;         float4* o = (float4*)(p.out + (size_t)m * DM + n);
;         float4 xv = *o;
;         *o = make_float4(xv.x + sigmoidf(a[0]) * bflo(pv.x), xv.y + sigmoidf(a[1]) * bfhi(pv.x),
;                          xv.z + sigmoidf(a[2]) * bflo(pv.y), xv.w + sigmoidf(a[3]) * bfhi(pv.y));
;       });
	v_rcp_f32_e32 v112, v29
	v_mul_f32_e32 v29, 0xbfb8aa3b, v109
	v_exp_f32_e32 v29, v29
	s_waitcnt vmcnt(5)
	v_lshlrev_b32_e32 v114, 16, v148
	v_add_f32_e32 v29, 1.0, v29
	v_rcp_f32_e32 v113, v29
	v_mul_f32_e32 v29, 0xbfb8aa3b, v106
	v_exp_f32_e32 v29, v29
	v_and_b32_e32 v115, 0xffff0000, v148
	v_lshlrev_b32_e32 v110, 16, v149
	v_and_b32_e32 v111, 0xffff0000, v149
	v_add_f32_e32 v29, 1.0, v29
	v_rcp_f32_e32 v116, v29
	v_mul_f32_e32 v29, 0xbfb8aa3b, v107

; DI float bflo(unsigned u) { return __uint_as_float(u << 16); }
; DI float bfhi(unsigned u) { return __uint_as_float(u & 0xffff0000u); }
; DI float sigmoidf(float x) { return __builtin_amdgcn_rcpf(1.f + __expf(-x)); }
; __global__ void __launch_bounds__(512, 2) mega(Params p) {
;     ...
;       gemm8_epi(acc8, m0, n0, [&](int m, int n, f32x4& a) {
;         uint2 pv = *(const uint2*)(ppb + (size_t)m * DM + n);
;         float4* o = (float4*)(p.out + (size_t)m * DM + n);
;         float4 xv = *o;
;         *o = make_float4(xv.x + sigmoidf(a[0]) * bflo(pv.x), xv.y + sigmoidf(a[1]) * bfhi(pv.x),
;                          xv.z + sigmoidf(a[2]) * bflo(pv.y), xv.w + sigmoidf(a[3]) * bfhi(pv.y));
;       });
	v_exp_f32_e32 v29, v29
	s_waitcnt vmcnt(4)
	v_pk_fma_f32 v[106:107], v[112:113], v[114:115], v[156:157]
	v_add_f32_e32 v29, 1.0, v29
	v_rcp_f32_e32 v117, v29
	v_mul_f32_e32 v29, 0xbfb8aa3b, v104
	v_exp_f32_e32 v29, v29
	v_pk_fma_f32 v[108:109], v[116:117], v[110:111], v[158:159]
	global_store_dwordx4 v[118:119], v[106:109], off offset:128
	v_add_f32_e32 v29, 1.0, v29

; DI float bflo(unsigned u) { return __uint_as_float(u << 16); }
; DI float bfhi(unsigned u) { return __uint_as_float(u & 0xffff0000u); }
; DI float sigmoidf(float x) { return __builtin_amdgcn_rcpf(1.f + __expf(-x)); }
; __global__ void __launch_bounds__(512, 2) mega(Params p) {
;     ...
;       gemm8_epi(acc8, m0, n0, [&](int m, int n, f32x4& a) {
;         uint2 pv = *(const uint2*)(ppb + (size_t)m * DM + n);
;         float4* o = (float4*)(p.out + (size_t)m * DM + n);
;         float4 xv = *o;
;         *o = make_float4(xv.x + sigmoidf(a[0]) * bflo(pv.x), xv.y + sigmoidf(a[1]) * bfhi(pv.x),
;                          xv.z + sigmoidf(a[2]) * bflo(pv.y), xv.w + sigmoidf(a[3]) * bfhi(pv.y));
;       });
	v_rcp_f32_e32 v108, v29
	v_mul_f32_e32 v29, 0xbfb8aa3b, v105
	v_exp_f32_e32 v29, v29
	s_waitcnt vmcnt(4)
	v_lshlrev_b32_e32 v110, 16, v150
	v_add_f32_e32 v29, 1.0, v29
	v_rcp_f32_e32 v109, v29
	v_mul_f32_e32 v29, 0xbfb8aa3b, v102
	v_exp_f32_e32 v29, v29
	v_and_b32_e32 v111, 0xffff0000, v150
	v_lshlrev_b32_e32 v106, 16, v151
	v_and_b32_e32 v107, 0xffff0000, v151
	v_add_f32_e32 v29, 1.0, v29
	v_rcp_f32_e32 v112, v29
	v_mul_f32_e32 v29, 0xbfb8aa3b, v103

; DI float bflo(unsigned u) { return __uint_as_float(u << 16); }
; DI float bfhi(unsigned u) { return __uint_as_float(u & 0xffff0000u); }
; DI float sigmoidf(float x) { return __builtin_amdgcn_rcpf(1.f + __expf(-x)); }
; template <class E>
; DI void gemm8_epi(f32x4 (&acc)[8][4], int m0, int n0, E e) {
;     ...
; #pragma unroll
;   for (int i = 0; i < 8; ++i)
; #pragma unroll
;     for (int j = 0; j < 4; ++j) {
;       const int m = m0 + wm * 128 + i * 16 + (lane & 15);
;       const int n = n0 + wn * 64 + j * 16 + (lane >> 4) * 4;
;       e(m, n, acc[i][j]);
;     }
; __global__ void __launch_bounds__(512, 2) mega(Params p) {
;     ...
;       gemm8_epi(acc8, m0, n0, [&](int m, int n, f32x4& a) {
;         uint2 pv = *(const uint2*)(ppb + (size_t)m * DM + n);
;         float4* o = (float4*)(p.out + (size_t)m * DM + n);
;         float4 xv = *o;
;         *o = make_float4(xv.x + sigmoidf(a[0]) * bflo(pv.x), xv.y + sigmoidf(a[1]) * bfhi(pv.x),
;                          xv.z + sigmoidf(a[2]) * bflo(pv.y), xv.w + sigmoidf(a[3]) * bfhi(pv.y));
;       });
	v_exp_f32_e32 v29, v29
	s_waitcnt vmcnt(3)
	v_pk_fma_f32 v[102:103], v[108:109], v[110:111], v[188:189]
	v_add_f32_e32 v29, 1.0, v29
	v_rcp_f32_e32 v113, v29
	v_mul_f32_e32 v29, 0xbfb8aa3b, v100
	v_exp_f32_e32 v29, v29
	v_pk_fma_f32 v[104:105], v[112:113], v[106:107], v[190:191]
	global_store_dwordx4 v[118:119], v[102:105], off offset:192
	v_add_f32_e32 v29, 1.0, v29
	v_rcp_f32_e32 v108, v29
	v_mul_f32_e32 v29, 0xbfb8aa3b, v101
	v_exp_f32_e32 v29, v29
	v_or_b32_e32 v102, 32, v28
	v_ashrrev_i32_e32 v103, 31, v102
	v_lshlrev_b64 v[104:105], 11, v[102:103]
	v_add_f32_e32 v29, 1.0, v29
	v_rcp_f32_e32 v109, v29
	v_mul_f32_e32 v29, 0xbfb8aa3b, v98
	v_exp_f32_e32 v29, v29
	v_lshl_add_u64 v[104:105], s[12:13], 0, v[104:105]
	v_lshlrev_b64 v[102:103], 12, v[102:103]
	v_lshl_add_u64 v[104:105], v[104:105], 0, v[0:1]
	v_lshl_add_u64 v[102:103], s[2:3], 0, v[102:103]
	global_load_dwordx2 v[106:107], v[104:105], off
	v_lshl_add_u64 v[102:103], v[102:103], 0, v[22:23]
	v_add_f32_e32 v29, 1.0, v29
	v_rcp_f32_e32 v112, v29
	v_mul_f32_e32 v29, 0xbfb8aa3b, v99
	global_load_dwordx4 v[98:101], v[102:103], off
	global_load_dwordx2 v[146:147], v[104:105], off offset:32
	global_load_dwordx4 v[152:155], v[102:103], off offset:64
	global_load_dwordx2 v[148:149], v[104:105], off offset:64
	global_load_dwordx4 v[156:159], v[102:103], off offset:128
	global_load_dwordx2 v[150:151], v[104:105], off offset:96
	global_load_dwordx4 v[188:191], v[102:103], off offset:192
	v_exp_f32_e32 v29, v29
	s_waitcnt vmcnt(7)
	v_lshlrev_b32_e32 v110, 16, v106
	v_add_f32_e32 v29, 1.0, v29
	v_rcp_f32_e32 v113, v29
	v_and_b32_e32 v111, 0xffff0000, v106
	v_lshlrev_b32_e32 v106, 16, v107
	v_and_b32_e32 v107, 0xffff0000, v107
	s_waitcnt vmcnt(6)
	v_pk_fma_f32 v[98:99], v[108:109], v[110:111], v[98:99]
	v_pk_fma_f32 v[100:101], v[112:113], v[106:107], v[100:101]
	global_store_dwordx4 v[102:103], v[98:101], off

; DI float bflo(unsigned u) { return __uint_as_float(u << 16); }
; DI float bfhi(unsigned u) { return __uint_as_float(u & 0xffff0000u); }
; DI float sigmoidf(float x) { return __builtin_amdgcn_rcpf(1.f + __expf(-x)); }
; __global__ void __launch_bounds__(512, 2) mega(Params p) {
;     ...
;       gemm8_epi(acc8, m0, n0, [&](int m, int n, f32x4& a) {
;         uint2 pv = *(const uint2*)(ppb + (size_t)m * DM + n);
;         float4* o = (float4*)(p.out + (size_t)m * DM + n);
;         float4 xv = *o;
;         *o = make_float4(xv.x + sigmoidf(a[0]) * bflo(pv.x), xv.y + sigmoidf(a[1]) * bfhi(pv.x),
;                          xv.z + sigmoidf(a[2]) * bflo(pv.y), xv.w + sigmoidf(a[3]) * bfhi(pv.y));
;       });
	v_mul_f32_e32 v29, 0xbfb8aa3b, v96

; DI float bflo(unsigned u) { return __uint_as_float(u << 16); }
; DI float bfhi(unsigned u) { return __uint_as_float(u & 0xffff0000u); }
; DI float sigmoidf(float x) { return __builtin_amdgcn_rcpf(1.f + __expf(-x)); }
; __global__ void __launch_bounds__(512, 2) mega(Params p) {
;     ...
;       gemm8_epi(acc8, m0, n0, [&](int m, int n, f32x4& a) {
;         uint2 pv = *(const uint2*)(ppb + (size_t)m * DM + n);
;         float4* o = (float4*)(p.out + (size_t)m * DM + n);
;         float4 xv = *o;
;         *o = make_float4(xv.x + sigmoidf(a[0]) * bflo(pv.x), xv.y + sigmoidf(a[1]) * bfhi(pv.x),
;                          xv.z + sigmoidf(a[2]) * bflo(pv.y), xv.w + sigmoidf(a[3]) * bfhi(pv.y));
;       });
	v_exp_f32_e32 v29, v29
	s_waitcnt vmcnt(6)
	v_lshlrev_b32_e32 v98, 16, v146
	v_add_f32_e32 v29, 1.0, v29
	v_rcp_f32_e32 v96, v29
	v_mul_f32_e32 v29, 0xbfb8aa3b, v97
	v_exp_f32_e32 v29, v29
	v_and_b32_e32 v99, 0xffff0000, v146
	v_lshlrev_b32_e32 v100, 16, v147
	v_and_b32_e32 v101, 0xffff0000, v147
	v_add_f32_e32 v29, 1.0, v29
	v_rcp_f32_e32 v97, v29
	v_mul_f32_e32 v29, 0xbfb8aa3b, v94
	v_exp_f32_e32 v29, v29
	s_waitcnt vmcnt(5)
	v_pk_fma_f32 v[96:97], v[96:97], v[98:99], v[152:153]
	v_add_f32_e32 v29, 1.0, v29
	v_rcp_f32_e32 v94, v29
	v_mul_f32_e32 v29, 0xbfb8aa3b, v95
	v_exp_f32_e32 v29, v29
	s_nop 0
	v_add_f32_e32 v29, 1.0, v29
	v_rcp_f32_e32 v95, v29
	v_mul_f32_e32 v29, 0xbfb8aa3b, v92
	v_exp_f32_e32 v29, v29
	v_pk_fma_f32 v[98:99], v[94:95], v[100:101], v[154:155]
	global_store_dwordx4 v[102:103], v[96:99], off offset:64
	v_add_f32_e32 v29, 1.0, v29

; DI float bflo(unsigned u) { return __uint_as_float(u << 16); }
; DI float bfhi(unsigned u) { return __uint_as_float(u & 0xffff0000u); }
; DI float sigmoidf(float x) { return __builtin_amdgcn_rcpf(1.f + __expf(-x)); }
; __global__ void __launch_bounds__(512, 2) mega(Params p) {
;     ...
;       gemm8_epi(acc8, m0, n0, [&](int m, int n, f32x4& a) {
;         uint2 pv = *(const uint2*)(ppb + (size_t)m * DM + n);
;         float4* o = (float4*)(p.out + (size_t)m * DM + n);
;         float4 xv = *o;
;         *o = make_float4(xv.x + sigmoidf(a[0]) * bflo(pv.x), xv.y + sigmoidf(a[1]) * bfhi(pv.x),
;                          xv.z + sigmoidf(a[2]) * bflo(pv.y), xv.w + sigmoidf(a[3]) * bfhi(pv.y));
;       });
	v_rcp_f32_e32 v96, v29
	v_mul_f32_e32 v29, 0xbfb8aa3b, v93
	v_exp_f32_e32 v29, v29
	s_waitcnt vmcnt(5)
	v_lshlrev_b32_e32 v98, 16, v148
	v_add_f32_e32 v29, 1.0, v29
	v_rcp_f32_e32 v97, v29
	v_mul_f32_e32 v29, 0xbfb8aa3b, v90
	v_exp_f32_e32 v29, v29
	v_and_b32_e32 v99, 0xffff0000, v148
	v_lshlrev_b32_e32 v94, 16, v149
	v_and_b32_e32 v95, 0xffff0000, v149
	v_add_f32_e32 v29, 1.0, v29
	v_rcp_f32_e32 v100, v29
	v_mul_f32_e32 v29, 0xbfb8aa3b, v91

; DI float bflo(unsigned u) { return __uint_as_float(u << 16); }
; DI float bfhi(unsigned u) { return __uint_as_float(u & 0xffff0000u); }
; DI float sigmoidf(float x) { return __builtin_amdgcn_rcpf(1.f + __expf(-x)); }
; __global__ void __launch_bounds__(512, 2) mega(Params p) {
;     ...
;       gemm8_epi(acc8, m0, n0, [&](int m, int n, f32x4& a) {
;         uint2 pv = *(const uint2*)(ppb + (size_t)m * DM + n);
;         float4* o = (float4*)(p.out + (size_t)m * DM + n);
;         float4 xv = *o;
;         *o = make_float4(xv.x + sigmoidf(a[0]) * bflo(pv.x), xv.y + sigmoidf(a[1]) * bfhi(pv.x),
;                          xv.z + sigmoidf(a[2]) * bflo(pv.y), xv.w + sigmoidf(a[3]) * bfhi(pv.y));
;       });
	v_exp_f32_e32 v29, v29
	s_waitcnt vmcnt(4)
	v_pk_fma_f32 v[90:91], v[96:97], v[98:99], v[156:157]
	v_add_f32_e32 v29, 1.0, v29
	v_rcp_f32_e32 v101, v29
	v_mul_f32_e32 v29, 0xbfb8aa3b, v88
	v_exp_f32_e32 v29, v29
	v_pk_fma_f32 v[92:93], v[100:101], v[94:95], v[158:159]
	global_store_dwordx4 v[102:103], v[90:93], off offset:128
	v_add_f32_e32 v29, 1.0, v29

; DI float bflo(unsigned u) { return __uint_as_float(u << 16); }
; DI float bfhi(unsigned u) { return __uint_as_float(u & 0xffff0000u); }
; DI float sigmoidf(float x) { return __builtin_amdgcn_rcpf(1.f + __expf(-x)); }
; __global__ void __launch_bounds__(512, 2) mega(Params p) {
;     ...
;       gemm8_epi(acc8, m0, n0, [&](int m, int n, f32x4& a) {
;         uint2 pv = *(const uint2*)(ppb + (size_t)m * DM + n);
;         float4* o = (float4*)(p.out + (size_t)m * DM + n);
;         float4 xv = *o;
;         *o = make_float4(xv.x + sigmoidf(a[0]) * bflo(pv.x), xv.y + sigmoidf(a[1]) * bfhi(pv.x),
;                          xv.z + sigmoidf(a[2]) * bflo(pv.y), xv.w + sigmoidf(a[3]) * bfhi(pv.y));
;       });
	v_rcp_f32_e32 v92, v29
	v_mul_f32_e32 v29, 0xbfb8aa3b, v89
	v_exp_f32_e32 v29, v29
	s_waitcnt vmcnt(4)
	v_lshlrev_b32_e32 v94, 16, v150
	v_add_f32_e32 v29, 1.0, v29
	v_rcp_f32_e32 v93, v29
	v_mul_f32_e32 v29, 0xbfb8aa3b, v86
	v_exp_f32_e32 v29, v29
	v_and_b32_e32 v95, 0xffff0000, v150
	v_lshlrev_b32_e32 v90, 16, v151
	v_and_b32_e32 v91, 0xffff0000, v151
	v_add_f32_e32 v29, 1.0, v29
	v_rcp_f32_e32 v96, v29
	v_mul_f32_e32 v29, 0xbfb8aa3b, v87

; DI float bflo(unsigned u) { return __uint_as_float(u << 16); }
; DI float bfhi(unsigned u) { return __uint_as_float(u & 0xffff0000u); }
; DI float sigmoidf(float x) { return __builtin_amdgcn_rcpf(1.f + __expf(-x)); }
; template <class E>
; DI void gemm8_epi(f32x4 (&acc)[8][4], int m0, int n0, E e) {
;     ...
; #pragma unroll
;   for (int i = 0; i < 8; ++i)
; #pragma unroll
;     for (int j = 0; j < 4; ++j) {
;       const int m = m0 + wm * 128 + i * 16 + (lane & 15);
;       const int n = n0 + wn * 64 + j * 16 + (lane >> 4) * 4;
;       e(m, n, acc[i][j]);
;     }
; __global__ void __launch_bounds__(512, 2) mega(Params p) {
;     ...
;       gemm8_epi(acc8, m0, n0, [&](int m, int n, f32x4& a) {
;         uint2 pv = *(const uint2*)(ppb + (size_t)m * DM + n);
;         float4* o = (float4*)(p.out + (size_t)m * DM + n);
;         float4 xv = *o;
;         *o = make_float4(xv.x + sigmoidf(a[0]) * bflo(pv.x), xv.y + sigmoidf(a[1]) * bfhi(pv.x),
;                          xv.z + sigmoidf(a[2]) * bflo(pv.y), xv.w + sigmoidf(a[3]) * bfhi(pv.y));
;       });
	v_exp_f32_e32 v29, v29
	s_waitcnt vmcnt(3)
	v_pk_fma_f32 v[86:87], v[92:93], v[94:95], v[188:189]
	v_add_f32_e32 v29, 1.0, v29
	v_rcp_f32_e32 v97, v29
	v_mul_f32_e32 v29, 0xbfb8aa3b, v84
	v_exp_f32_e32 v29, v29
	v_pk_fma_f32 v[88:89], v[96:97], v[90:91], v[190:191]
	global_store_dwordx4 v[102:103], v[86:89], off offset:192
	v_add_f32_e32 v29, 1.0, v29
	v_rcp_f32_e32 v92, v29
	v_mul_f32_e32 v29, 0xbfb8aa3b, v85
	v_exp_f32_e32 v29, v29
	v_or_b32_e32 v86, 48, v28
	v_ashrrev_i32_e32 v87, 31, v86
	v_lshlrev_b64 v[88:89], 11, v[86:87]
	v_add_f32_e32 v29, 1.0, v29
	v_rcp_f32_e32 v93, v29
	v_mul_f32_e32 v29, 0xbfb8aa3b, v82
	v_exp_f32_e32 v29, v29
	v_lshl_add_u64 v[88:89], s[12:13], 0, v[88:89]
	v_lshlrev_b64 v[86:87], 12, v[86:87]
	v_lshl_add_u64 v[88:89], v[88:89], 0, v[0:1]
	v_lshl_add_u64 v[86:87], s[2:3], 0, v[86:87]
	global_load_dwordx2 v[90:91], v[88:89], off
	v_lshl_add_u64 v[86:87], v[86:87], 0, v[22:23]
	v_add_f32_e32 v29, 1.0, v29
	v_rcp_f32_e32 v96, v29
	v_mul_f32_e32 v29, 0xbfb8aa3b, v83
	global_load_dwordx4 v[82:85], v[86:87], off
	global_load_dwordx2 v[146:147], v[88:89], off offset:32
	global_load_dwordx4 v[152:155], v[86:87], off offset:64
	global_load_dwordx2 v[148:149], v[88:89], off offset:64
	global_load_dwordx4 v[156:159], v[86:87], off offset:128
	global_load_dwordx2 v[150:151], v[88:89], off offset:96
	global_load_dwordx4 v[188:191], v[86:87], off offset:192
	v_exp_f32_e32 v29, v29
	s_waitcnt vmcnt(7)
	v_lshlrev_b32_e32 v94, 16, v90
	v_add_f32_e32 v29, 1.0, v29
	v_rcp_f32_e32 v97, v29
	v_and_b32_e32 v95, 0xffff0000, v90
	v_lshlrev_b32_e32 v90, 16, v91
	v_and_b32_e32 v91, 0xffff0000, v91
	s_waitcnt vmcnt(6)
	v_pk_fma_f32 v[82:83], v[92:93], v[94:95], v[82:83]
	v_pk_fma_f32 v[84:85], v[96:97], v[90:91], v[84:85]
	global_store_dwordx4 v[86:87], v[82:85], off

; DI float bflo(unsigned u) { return __uint_as_float(u << 16); }
; DI float bfhi(unsigned u) { return __uint_as_float(u & 0xffff0000u); }
; DI float sigmoidf(float x) { return __builtin_amdgcn_rcpf(1.f + __expf(-x)); }
; __global__ void __launch_bounds__(512, 2) mega(Params p) {
;     ...
;       gemm8_epi(acc8, m0, n0, [&](int m, int n, f32x4& a) {
;         uint2 pv = *(const uint2*)(ppb + (size_t)m * DM + n);
;         float4* o = (float4*)(p.out + (size_t)m * DM + n);
;         float4 xv = *o;
;         *o = make_float4(xv.x + sigmoidf(a[0]) * bflo(pv.x), xv.y + sigmoidf(a[1]) * bfhi(pv.x),
;                          xv.z + sigmoidf(a[2]) * bflo(pv.y), xv.w + sigmoidf(a[3]) * bfhi(pv.y));
;       });
	v_mul_f32_e32 v29, 0xbfb8aa3b, v80

; DI float bflo(unsigned u) { return __uint_as_float(u << 16); }
; DI float bfhi(unsigned u) { return __uint_as_float(u & 0xffff0000u); }
; DI float sigmoidf(float x) { return __builtin_amdgcn_rcpf(1.f + __expf(-x)); }
; __global__ void __launch_bounds__(512, 2) mega(Params p) {
;     ...
;       gemm8_epi(acc8, m0, n0, [&](int m, int n, f32x4& a) {
;         uint2 pv = *(const uint2*)(ppb + (size_t)m * DM + n);
;         float4* o = (float4*)(p.out + (size_t)m * DM + n);
;         float4 xv = *o;
;         *o = make_float4(xv.x + sigmoidf(a[0]) * bflo(pv.x), xv.y + sigmoidf(a[1]) * bfhi(pv.x),
;                          xv.z + sigmoidf(a[2]) * bflo(pv.y), xv.w + sigmoidf(a[3]) * bfhi(pv.y));
;       });
	v_exp_f32_e32 v29, v29
	s_waitcnt vmcnt(6)
	v_lshlrev_b32_e32 v82, 16, v146
	v_add_f32_e32 v29, 1.0, v29
	v_rcp_f32_e32 v80, v29
	v_mul_f32_e32 v29, 0xbfb8aa3b, v81
	v_exp_f32_e32 v29, v29
	v_and_b32_e32 v83, 0xffff0000, v146
	v_lshlrev_b32_e32 v84, 16, v147
	v_and_b32_e32 v85, 0xffff0000, v147
	v_add_f32_e32 v29, 1.0, v29
	v_rcp_f32_e32 v81, v29
	v_mul_f32_e32 v29, 0xbfb8aa3b, v78
	v_exp_f32_e32 v29, v29
	s_waitcnt vmcnt(5)
	v_pk_fma_f32 v[80:81], v[80:81], v[82:83], v[152:153]
	v_add_f32_e32 v29, 1.0, v29
	v_rcp_f32_e32 v78, v29
	v_mul_f32_e32 v29, 0xbfb8aa3b, v79
	v_exp_f32_e32 v29, v29
	s_nop 0
	v_add_f32_e32 v29, 1.0, v29
	v_rcp_f32_e32 v79, v29
	v_mul_f32_e32 v29, 0xbfb8aa3b, v76
	v_exp_f32_e32 v29, v29
	v_pk_fma_f32 v[82:83], v[78:79], v[84:85], v[154:155]
	global_store_dwordx4 v[86:87], v[80:83], off offset:64
	v_add_f32_e32 v29, 1.0, v29

; DI float bflo(unsigned u) { return __uint_as_float(u << 16); }
; DI float bfhi(unsigned u) { return __uint_as_float(u & 0xffff0000u); }
; DI float sigmoidf(float x) { return __builtin_amdgcn_rcpf(1.f + __expf(-x)); }
; __global__ void __launch_bounds__(512, 2) mega(Params p) {
;     ...
;       gemm8_epi(acc8, m0, n0, [&](int m, int n, f32x4& a) {
;         uint2 pv = *(const uint2*)(ppb + (size_t)m * DM + n);
;         float4* o = (float4*)(p.out + (size_t)m * DM + n);
;         float4 xv = *o;
;         *o = make_float4(xv.x + sigmoidf(a[0]) * bflo(pv.x), xv.y + sigmoidf(a[1]) * bfhi(pv.x),
;                          xv.z + sigmoidf(a[2]) * bflo(pv.y), xv.w + sigmoidf(a[3]) * bfhi(pv.y));
;       });
	v_rcp_f32_e32 v80, v29
	v_mul_f32_e32 v29, 0xbfb8aa3b, v77
	v_exp_f32_e32 v29, v29
	s_waitcnt vmcnt(5)
	v_lshlrev_b32_e32 v82, 16, v148
	v_add_f32_e32 v29, 1.0, v29
	v_rcp_f32_e32 v81, v29
	v_mul_f32_e32 v29, 0xbfb8aa3b, v74
	v_exp_f32_e32 v29, v29
	v_and_b32_e32 v83, 0xffff0000, v148
	v_lshlrev_b32_e32 v78, 16, v149
	v_and_b32_e32 v79, 0xffff0000, v149
	v_add_f32_e32 v29, 1.0, v29
	v_rcp_f32_e32 v84, v29
	v_mul_f32_e32 v29, 0xbfb8aa3b, v75

; DI float bflo(unsigned u) { return __uint_as_float(u << 16); }
; DI float bfhi(unsigned u) { return __uint_as_float(u & 0xffff0000u); }
; DI float sigmoidf(float x) { return __builtin_amdgcn_rcpf(1.f + __expf(-x)); }
; __global__ void __launch_bounds__(512, 2) mega(Params p) {
;     ...
;       gemm8_epi(acc8, m0, n0, [&](int m, int n, f32x4& a) {
;         uint2 pv = *(const uint2*)(ppb + (size_t)m * DM + n);
;         float4* o = (float4*)(p.out + (size_t)m * DM + n);
;         float4 xv = *o;
;         *o = make_float4(xv.x + sigmoidf(a[0]) * bflo(pv.x), xv.y + sigmoidf(a[1]) * bfhi(pv.x),
;                          xv.z + sigmoidf(a[2]) * bflo(pv.y), xv.w + sigmoidf(a[3]) * bfhi(pv.y));
;       });
	v_exp_f32_e32 v29, v29
	s_waitcnt vmcnt(4)
	v_pk_fma_f32 v[74:75], v[80:81], v[82:83], v[156:157]
	v_add_f32_e32 v29, 1.0, v29
	v_rcp_f32_e32 v85, v29
	v_mul_f32_e32 v29, 0xbfb8aa3b, v72
	v_exp_f32_e32 v29, v29
	v_pk_fma_f32 v[76:77], v[84:85], v[78:79], v[158:159]
	global_store_dwordx4 v[86:87], v[74:77], off offset:128
	v_add_f32_e32 v29, 1.0, v29

; DI float bflo(unsigned u) { return __uint_as_float(u << 16); }
; DI float bfhi(unsigned u) { return __uint_as_float(u & 0xffff0000u); }
; DI float sigmoidf(float x) { return __builtin_amdgcn_rcpf(1.f + __expf(-x)); }
; __global__ void __launch_bounds__(512, 2) mega(Params p) {
;     ...
;       gemm8_epi(acc8, m0, n0, [&](int m, int n, f32x4& a) {
;         uint2 pv = *(const uint2*)(ppb + (size_t)m * DM + n);
;         float4* o = (float4*)(p.out + (size_t)m * DM + n);
;         float4 xv = *o;
;         *o = make_float4(xv.x + sigmoidf(a[0]) * bflo(pv.x), xv.y + sigmoidf(a[1]) * bfhi(pv.x),
;                          xv.z + sigmoidf(a[2]) * bflo(pv.y), xv.w + sigmoidf(a[3]) * bfhi(pv.y));
;       });
	v_rcp_f32_e32 v76, v29
	v_mul_f32_e32 v29, 0xbfb8aa3b, v73
	v_exp_f32_e32 v29, v29
	s_waitcnt vmcnt(4)
	v_lshlrev_b32_e32 v78, 16, v150
	v_add_f32_e32 v29, 1.0, v29
	v_rcp_f32_e32 v77, v29
	v_mul_f32_e32 v29, 0xbfb8aa3b, v70
	v_exp_f32_e32 v29, v29
	v_and_b32_e32 v79, 0xffff0000, v150
	v_lshlrev_b32_e32 v74, 16, v151
	v_and_b32_e32 v75, 0xffff0000, v151
	v_add_f32_e32 v29, 1.0, v29
	v_rcp_f32_e32 v80, v29
	v_mul_f32_e32 v29, 0xbfb8aa3b, v71

; DI float bflo(unsigned u) { return __uint_as_float(u << 16); }
; DI float bfhi(unsigned u) { return __uint_as_float(u & 0xffff0000u); }
; DI float sigmoidf(float x) { return __builtin_amdgcn_rcpf(1.f + __expf(-x)); }
; template <class E>
; DI void gemm8_epi(f32x4 (&acc)[8][4], int m0, int n0, E e) {
;     ...
; #pragma unroll
;   for (int i = 0; i < 8; ++i)
; #pragma unroll
;     for (int j = 0; j < 4; ++j) {
;       const int m = m0 + wm * 128 + i * 16 + (lane & 15);
;       const int n = n0 + wn * 64 + j * 16 + (lane >> 4) * 4;
;       e(m, n, acc[i][j]);
;     }
; __global__ void __launch_bounds__(512, 2) mega(Params p) {
;     ...
;       gemm8_epi(acc8, m0, n0, [&](int m, int n, f32x4& a) {
;         uint2 pv = *(const uint2*)(ppb + (size_t)m * DM + n);
;         float4* o = (float4*)(p.out + (size_t)m * DM + n);
;         float4 xv = *o;
;         *o = make_float4(xv.x + sigmoidf(a[0]) * bflo(pv.x), xv.y + sigmoidf(a[1]) * bfhi(pv.x),
;                          xv.z + sigmoidf(a[2]) * bflo(pv.y), xv.w + sigmoidf(a[3]) * bfhi(pv.y));
;       });
	v_exp_f32_e32 v29, v29
	s_waitcnt vmcnt(3)
	v_pk_fma_f32 v[70:71], v[76:77], v[78:79], v[188:189]
	v_add_f32_e32 v29, 1.0, v29
	v_rcp_f32_e32 v81, v29
	v_mul_f32_e32 v29, 0xbfb8aa3b, v68
	v_exp_f32_e32 v29, v29
	v_pk_fma_f32 v[72:73], v[80:81], v[74:75], v[190:191]
	global_store_dwordx4 v[86:87], v[70:73], off offset:192
	v_add_f32_e32 v29, 1.0, v29
	v_rcp_f32_e32 v76, v29
	v_mul_f32_e32 v29, 0xbfb8aa3b, v69
	v_exp_f32_e32 v29, v29
	v_or_b32_e32 v70, 64, v28
	v_ashrrev_i32_e32 v71, 31, v70
	v_lshlrev_b64 v[72:73], 11, v[70:71]
	v_add_f32_e32 v29, 1.0, v29
	v_rcp_f32_e32 v77, v29
	v_mul_f32_e32 v29, 0xbfb8aa3b, v66
	v_exp_f32_e32 v29, v29
	v_lshl_add_u64 v[72:73], s[12:13], 0, v[72:73]
	v_lshlrev_b64 v[70:71], 12, v[70:71]
	v_lshl_add_u64 v[72:73], v[72:73], 0, v[0:1]
	v_lshl_add_u64 v[70:71], s[2:3], 0, v[70:71]
	global_load_dwordx2 v[74:75], v[72:73], off
	v_lshl_add_u64 v[70:71], v[70:71], 0, v[22:23]
	v_add_f32_e32 v29, 1.0, v29
	v_rcp_f32_e32 v80, v29
	v_mul_f32_e32 v29, 0xbfb8aa3b, v67
	global_load_dwordx4 v[66:69], v[70:71], off
	global_load_dwordx2 v[146:147], v[72:73], off offset:32
	global_load_dwordx4 v[152:155], v[70:71], off offset:64
	global_load_dwordx2 v[148:149], v[72:73], off offset:64
	global_load_dwordx4 v[156:159], v[70:71], off offset:128
	global_load_dwordx2 v[150:151], v[72:73], off offset:96
	global_load_dwordx4 v[188:191], v[70:71], off offset:192
	v_exp_f32_e32 v29, v29
	s_waitcnt vmcnt(7)
	v_lshlrev_b32_e32 v78, 16, v74
	v_add_f32_e32 v29, 1.0, v29
	v_rcp_f32_e32 v81, v29
	v_and_b32_e32 v79, 0xffff0000, v74
	v_lshlrev_b32_e32 v74, 16, v75
	v_and_b32_e32 v75, 0xffff0000, v75
	s_waitcnt vmcnt(6)
	v_pk_fma_f32 v[66:67], v[76:77], v[78:79], v[66:67]
	v_pk_fma_f32 v[68:69], v[80:81], v[74:75], v[68:69]
	global_store_dwordx4 v[70:71], v[66:69], off

; DI float bflo(unsigned u) { return __uint_as_float(u << 16); }
; DI float bfhi(unsigned u) { return __uint_as_float(u & 0xffff0000u); }
; DI float sigmoidf(float x) { return __builtin_amdgcn_rcpf(1.f + __expf(-x)); }
; __global__ void __launch_bounds__(512, 2) mega(Params p) {
;     ...
;       gemm8_epi(acc8, m0, n0, [&](int m, int n, f32x4& a) {
;         uint2 pv = *(const uint2*)(ppb + (size_t)m * DM + n);
;         float4* o = (float4*)(p.out + (size_t)m * DM + n);
;         float4 xv = *o;
;         *o = make_float4(xv.x + sigmoidf(a[0]) * bflo(pv.x), xv.y + sigmoidf(a[1]) * bfhi(pv.x),
;                          xv.z + sigmoidf(a[2]) * bflo(pv.y), xv.w + sigmoidf(a[3]) * bfhi(pv.y));
;       });
	v_mul_f32_e32 v29, 0xbfb8aa3b, v64

; DI float bflo(unsigned u) { return __uint_as_float(u << 16); }
; DI float bfhi(unsigned u) { return __uint_as_float(u & 0xffff0000u); }
; DI float sigmoidf(float x) { return __builtin_amdgcn_rcpf(1.f + __expf(-x)); }
; __global__ void __launch_bounds__(512, 2) mega(Params p) {
;     ...
;       gemm8_epi(acc8, m0, n0, [&](int m, int n, f32x4& a) {
;         uint2 pv = *(const uint2*)(ppb + (size_t)m * DM + n);
;         float4* o = (float4*)(p.out + (size_t)m * DM + n);
;         float4 xv = *o;
;         *o = make_float4(xv.x + sigmoidf(a[0]) * bflo(pv.x), xv.y + sigmoidf(a[1]) * bfhi(pv.x),
;                          xv.z + sigmoidf(a[2]) * bflo(pv.y), xv.w + sigmoidf(a[3]) * bfhi(pv.y));
;       });
	v_exp_f32_e32 v29, v29
	s_waitcnt vmcnt(6)
	v_lshlrev_b32_e32 v66, 16, v146
	v_add_f32_e32 v29, 1.0, v29
	v_rcp_f32_e32 v64, v29
	v_mul_f32_e32 v29, 0xbfb8aa3b, v65
	v_exp_f32_e32 v29, v29
	v_and_b32_e32 v67, 0xffff0000, v146
	v_lshlrev_b32_e32 v68, 16, v147
	v_and_b32_e32 v69, 0xffff0000, v147
	v_add_f32_e32 v29, 1.0, v29
	v_rcp_f32_e32 v65, v29
	v_mul_f32_e32 v29, 0xbfb8aa3b, v62
	v_exp_f32_e32 v29, v29
	s_waitcnt vmcnt(5)
	v_pk_fma_f32 v[64:65], v[64:65], v[66:67], v[152:153]
	v_add_f32_e32 v29, 1.0, v29
	v_rcp_f32_e32 v62, v29
	v_mul_f32_e32 v29, 0xbfb8aa3b, v63
	v_exp_f32_e32 v29, v29
	s_nop 0
	v_add_f32_e32 v29, 1.0, v29
	v_rcp_f32_e32 v63, v29
	v_mul_f32_e32 v29, 0xbfb8aa3b, v60
	v_exp_f32_e32 v29, v29
	v_pk_fma_f32 v[66:67], v[62:63], v[68:69], v[154:155]
	global_store_dwordx4 v[70:71], v[64:67], off offset:64
	v_add_f32_e32 v29, 1.0, v29

; DI float bflo(unsigned u) { return __uint_as_float(u << 16); }
; DI float bfhi(unsigned u) { return __uint_as_float(u & 0xffff0000u); }
; DI float sigmoidf(float x) { return __builtin_amdgcn_rcpf(1.f + __expf(-x)); }
; __global__ void __launch_bounds__(512, 2) mega(Params p) {
;     ...
;       gemm8_epi(acc8, m0, n0, [&](int m, int n, f32x4& a) {
;         uint2 pv = *(const uint2*)(ppb + (size_t)m * DM + n);
;         float4* o = (float4*)(p.out + (size_t)m * DM + n);
;         float4 xv = *o;
;         *o = make_float4(xv.x + sigmoidf(a[0]) * bflo(pv.x), xv.y + sigmoidf(a[1]) * bfhi(pv.x),
;                          xv.z + sigmoidf(a[2]) * bflo(pv.y), xv.w + sigmoidf(a[3]) * bfhi(pv.y));
;       });
	v_rcp_f32_e32 v64, v29
	v_mul_f32_e32 v29, 0xbfb8aa3b, v61
	v_exp_f32_e32 v29, v29
	s_waitcnt vmcnt(5)
	v_lshlrev_b32_e32 v66, 16, v148
	v_add_f32_e32 v29, 1.0, v29
	v_rcp_f32_e32 v65, v29
	v_mul_f32_e32 v29, 0xbfb8aa3b, v58
	v_exp_f32_e32 v29, v29
	v_and_b32_e32 v67, 0xffff0000, v148
	v_lshlrev_b32_e32 v62, 16, v149
	v_and_b32_e32 v63, 0xffff0000, v149
	v_add_f32_e32 v29, 1.0, v29
	v_rcp_f32_e32 v68, v29
	v_mul_f32_e32 v29, 0xbfb8aa3b, v59

; DI float bflo(unsigned u) { return __uint_as_float(u << 16); }
; DI float bfhi(unsigned u) { return __uint_as_float(u & 0xffff0000u); }
; DI float sigmoidf(float x) { return __builtin_amdgcn_rcpf(1.f + __expf(-x)); }
; __global__ void __launch_bounds__(512, 2) mega(Params p) {
;     ...
;       gemm8_epi(acc8, m0, n0, [&](int m, int n, f32x4& a) {
;         uint2 pv = *(const uint2*)(ppb + (size_t)m * DM + n);
;         float4* o = (float4*)(p.out + (size_t)m * DM + n);
;         float4 xv = *o;
;         *o = make_float4(xv.x + sigmoidf(a[0]) * bflo(pv.x), xv.y + sigmoidf(a[1]) * bfhi(pv.x),
;                          xv.z + sigmoidf(a[2]) * bflo(pv.y), xv.w + sigmoidf(a[3]) * bfhi(pv.y));
;       });
	v_exp_f32_e32 v29, v29
	s_waitcnt vmcnt(4)
	v_pk_fma_f32 v[58:59], v[64:65], v[66:67], v[156:157]
	v_add_f32_e32 v29, 1.0, v29
	v_rcp_f32_e32 v69, v29
	v_mul_f32_e32 v29, 0xbfb8aa3b, v56
	v_exp_f32_e32 v29, v29
	v_pk_fma_f32 v[60:61], v[68:69], v[62:63], v[158:159]
	global_store_dwordx4 v[70:71], v[58:61], off offset:128
	v_add_f32_e32 v29, 1.0, v29

; DI float bflo(unsigned u) { return __uint_as_float(u << 16); }
; DI float bfhi(unsigned u) { return __uint_as_float(u & 0xffff0000u); }
; DI float sigmoidf(float x) { return __builtin_amdgcn_rcpf(1.f + __expf(-x)); }
; __global__ void __launch_bounds__(512, 2) mega(Params p) {
;     ...
;       gemm8_epi(acc8, m0, n0, [&](int m, int n, f32x4& a) {
;         uint2 pv = *(const uint2*)(ppb + (size_t)m * DM + n);
;         float4* o = (float4*)(p.out + (size_t)m * DM + n);
;         float4 xv = *o;
;         *o = make_float4(xv.x + sigmoidf(a[0]) * bflo(pv.x), xv.y + sigmoidf(a[1]) * bfhi(pv.x),
;                          xv.z + sigmoidf(a[2]) * bflo(pv.y), xv.w + sigmoidf(a[3]) * bfhi(pv.y));
;       });
	v_rcp_f32_e32 v60, v29
	v_mul_f32_e32 v29, 0xbfb8aa3b, v57
	v_exp_f32_e32 v29, v29
	s_waitcnt vmcnt(4)
	v_lshlrev_b32_e32 v62, 16, v150
	v_add_f32_e32 v29, 1.0, v29
	v_rcp_f32_e32 v61, v29
	v_mul_f32_e32 v29, 0xbfb8aa3b, v54
	v_exp_f32_e32 v29, v29
	v_and_b32_e32 v63, 0xffff0000, v150
	v_lshlrev_b32_e32 v58, 16, v151
	v_and_b32_e32 v59, 0xffff0000, v151
	v_add_f32_e32 v29, 1.0, v29
	v_rcp_f32_e32 v64, v29
	v_mul_f32_e32 v29, 0xbfb8aa3b, v55

; DI float bflo(unsigned u) { return __uint_as_float(u << 16); }
; DI float bfhi(unsigned u) { return __uint_as_float(u & 0xffff0000u); }
; DI float sigmoidf(float x) { return __builtin_amdgcn_rcpf(1.f + __expf(-x)); }
; template <class E>
; DI void gemm8_epi(f32x4 (&acc)[8][4], int m0, int n0, E e) {
;     ...
; #pragma unroll
;   for (int i = 0; i < 8; ++i)
; #pragma unroll
;     for (int j = 0; j < 4; ++j) {
;       const int m = m0 + wm * 128 + i * 16 + (lane & 15);
;       const int n = n0 + wn * 64 + j * 16 + (lane >> 4) * 4;
;       e(m, n, acc[i][j]);
;     }
; __global__ void __launch_bounds__(512, 2) mega(Params p) {
;     ...
;       gemm8_epi(acc8, m0, n0, [&](int m, int n, f32x4& a) {
;         uint2 pv = *(const uint2*)(ppb + (size_t)m * DM + n);
;         float4* o = (float4*)(p.out + (size_t)m * DM + n);
;         float4 xv = *o;
;         *o = make_float4(xv.x + sigmoidf(a[0]) * bflo(pv.x), xv.y + sigmoidf(a[1]) * bfhi(pv.x),
;                          xv.z + sigmoidf(a[2]) * bflo(pv.y), xv.w + sigmoidf(a[3]) * bfhi(pv.y));
;       });
	v_exp_f32_e32 v29, v29
	s_waitcnt vmcnt(3)
	v_pk_fma_f32 v[54:55], v[60:61], v[62:63], v[188:189]
	v_add_f32_e32 v29, 1.0, v29
	v_rcp_f32_e32 v65, v29
	v_mul_f32_e32 v29, 0xbfb8aa3b, v52
	v_exp_f32_e32 v29, v29
	v_pk_fma_f32 v[56:57], v[64:65], v[58:59], v[190:191]
	global_store_dwordx4 v[70:71], v[54:57], off offset:192
	v_add_f32_e32 v29, 1.0, v29
	v_rcp_f32_e32 v60, v29
	v_mul_f32_e32 v29, 0xbfb8aa3b, v53
	v_exp_f32_e32 v29, v29
	v_or_b32_e32 v54, 0x50, v28
	v_ashrrev_i32_e32 v55, 31, v54
	v_lshlrev_b64 v[56:57], 11, v[54:55]
	v_add_f32_e32 v29, 1.0, v29
	v_rcp_f32_e32 v61, v29
	v_mul_f32_e32 v29, 0xbfb8aa3b, v50
	v_exp_f32_e32 v29, v29
	v_lshl_add_u64 v[56:57], s[12:13], 0, v[56:57]
	v_lshlrev_b64 v[54:55], 12, v[54:55]
	v_lshl_add_u64 v[56:57], v[56:57], 0, v[0:1]
	v_lshl_add_u64 v[54:55], s[2:3], 0, v[54:55]
	global_load_dwordx2 v[58:59], v[56:57], off
	v_lshl_add_u64 v[54:55], v[54:55], 0, v[22:23]
	v_add_f32_e32 v29, 1.0, v29
	v_rcp_f32_e32 v64, v29
	v_mul_f32_e32 v29, 0xbfb8aa3b, v51
	global_load_dwordx4 v[50:53], v[54:55], off
	global_load_dwordx2 v[146:147], v[56:57], off offset:32
	global_load_dwordx4 v[152:155], v[54:55], off offset:64
	global_load_dwordx2 v[148:149], v[56:57], off offset:64
	global_load_dwordx4 v[156:159], v[54:55], off offset:128
	global_load_dwordx2 v[150:151], v[56:57], off offset:96
	global_load_dwordx4 v[188:191], v[54:55], off offset:192
	v_exp_f32_e32 v29, v29
	s_waitcnt vmcnt(7)
	v_lshlrev_b32_e32 v62, 16, v58
	v_add_f32_e32 v29, 1.0, v29
	v_rcp_f32_e32 v65, v29
	v_and_b32_e32 v63, 0xffff0000, v58
	v_lshlrev_b32_e32 v58, 16, v59
	v_and_b32_e32 v59, 0xffff0000, v59
	s_waitcnt vmcnt(6)
	v_pk_fma_f32 v[50:51], v[60:61], v[62:63], v[50:51]
	v_pk_fma_f32 v[52:53], v[64:65], v[58:59], v[52:53]
	global_store_dwordx4 v[54:55], v[50:53], off

; DI float bflo(unsigned u) { return __uint_as_float(u << 16); }
; DI float bfhi(unsigned u) { return __uint_as_float(u & 0xffff0000u); }
; DI float sigmoidf(float x) { return __builtin_amdgcn_rcpf(1.f + __expf(-x)); }
; __global__ void __launch_bounds__(512, 2) mega(Params p) {
;     ...
;       gemm8_epi(acc8, m0, n0, [&](int m, int n, f32x4& a) {
;         uint2 pv = *(const uint2*)(ppb + (size_t)m * DM + n);
;         float4* o = (float4*)(p.out + (size_t)m * DM + n);
;         float4 xv = *o;
;         *o = make_float4(xv.x + sigmoidf(a[0]) * bflo(pv.x), xv.y + sigmoidf(a[1]) * bfhi(pv.x),
;                          xv.z + sigmoidf(a[2]) * bflo(pv.y), xv.w + sigmoidf(a[3]) * bfhi(pv.y));
;       });
	v_mul_f32_e32 v29, 0xbfb8aa3b, v48

; DI float bflo(unsigned u) { return __uint_as_float(u << 16); }
; DI float bfhi(unsigned u) { return __uint_as_float(u & 0xffff0000u); }
; DI float sigmoidf(float x) { return __builtin_amdgcn_rcpf(1.f + __expf(-x)); }
; __global__ void __launch_bounds__(512, 2) mega(Params p) {
;     ...
;       gemm8_epi(acc8, m0, n0, [&](int m, int n, f32x4& a) {
;         uint2 pv = *(const uint2*)(ppb + (size_t)m * DM + n);
;         float4* o = (float4*)(p.out + (size_t)m * DM + n);
;         float4 xv = *o;
;         *o = make_float4(xv.x + sigmoidf(a[0]) * bflo(pv.x), xv.y + sigmoidf(a[1]) * bfhi(pv.x),
;                          xv.z + sigmoidf(a[2]) * bflo(pv.y), xv.w + sigmoidf(a[3]) * bfhi(pv.y));
;       });
	v_exp_f32_e32 v29, v29
	s_waitcnt vmcnt(6)
	v_lshlrev_b32_e32 v50, 16, v146
	v_add_f32_e32 v29, 1.0, v29
	v_rcp_f32_e32 v48, v29
	v_mul_f32_e32 v29, 0xbfb8aa3b, v49
	v_exp_f32_e32 v29, v29
	v_and_b32_e32 v51, 0xffff0000, v146
	v_lshlrev_b32_e32 v52, 16, v147
	v_and_b32_e32 v53, 0xffff0000, v147
	v_add_f32_e32 v29, 1.0, v29
	v_rcp_f32_e32 v49, v29
	v_mul_f32_e32 v29, 0xbfb8aa3b, v46
	v_exp_f32_e32 v29, v29
	s_waitcnt vmcnt(5)
	v_pk_fma_f32 v[48:49], v[48:49], v[50:51], v[152:153]
	v_add_f32_e32 v29, 1.0, v29
	v_rcp_f32_e32 v46, v29
	v_mul_f32_e32 v29, 0xbfb8aa3b, v47
	v_exp_f32_e32 v29, v29
	s_nop 0
	v_add_f32_e32 v29, 1.0, v29
	v_rcp_f32_e32 v47, v29
	v_mul_f32_e32 v29, 0xbfb8aa3b, v44
	v_exp_f32_e32 v29, v29
	v_pk_fma_f32 v[50:51], v[46:47], v[52:53], v[154:155]
	global_store_dwordx4 v[54:55], v[48:51], off offset:64
	v_add_f32_e32 v29, 1.0, v29

; DI float bflo(unsigned u) { return __uint_as_float(u << 16); }
; DI float bfhi(unsigned u) { return __uint_as_float(u & 0xffff0000u); }
; DI float sigmoidf(float x) { return __builtin_amdgcn_rcpf(1.f + __expf(-x)); }
; __global__ void __launch_bounds__(512, 2) mega(Params p) {
;     ...
;       gemm8_epi(acc8, m0, n0, [&](int m, int n, f32x4& a) {
;         uint2 pv = *(const uint2*)(ppb + (size_t)m * DM + n);
;         float4* o = (float4*)(p.out + (size_t)m * DM + n);
;         float4 xv = *o;
;         *o = make_float4(xv.x + sigmoidf(a[0]) * bflo(pv.x), xv.y + sigmoidf(a[1]) * bfhi(pv.x),
;                          xv.z + sigmoidf(a[2]) * bflo(pv.y), xv.w + sigmoidf(a[3]) * bfhi(pv.y));
;       });
	v_rcp_f32_e32 v48, v29
	v_mul_f32_e32 v29, 0xbfb8aa3b, v45
	v_exp_f32_e32 v29, v29
	s_waitcnt vmcnt(5)
	v_lshlrev_b32_e32 v50, 16, v148
	v_add_f32_e32 v29, 1.0, v29
	v_rcp_f32_e32 v49, v29
	v_mul_f32_e32 v29, 0xbfb8aa3b, v42
	v_exp_f32_e32 v29, v29
	v_and_b32_e32 v51, 0xffff0000, v148
	v_lshlrev_b32_e32 v46, 16, v149
	v_and_b32_e32 v47, 0xffff0000, v149
	v_add_f32_e32 v29, 1.0, v29
	v_rcp_f32_e32 v52, v29
	v_mul_f32_e32 v29, 0xbfb8aa3b, v43

; DI float bflo(unsigned u) { return __uint_as_float(u << 16); }
; DI float bfhi(unsigned u) { return __uint_as_float(u & 0xffff0000u); }
; DI float sigmoidf(float x) { return __builtin_amdgcn_rcpf(1.f + __expf(-x)); }
; __global__ void __launch_bounds__(512, 2) mega(Params p) {
;     ...
;       gemm8_epi(acc8, m0, n0, [&](int m, int n, f32x4& a) {
;         uint2 pv = *(const uint2*)(ppb + (size_t)m * DM + n);
;         float4* o = (float4*)(p.out + (size_t)m * DM + n);
;         float4 xv = *o;
;         *o = make_float4(xv.x + sigmoidf(a[0]) * bflo(pv.x), xv.y + sigmoidf(a[1]) * bfhi(pv.x),
;                          xv.z + sigmoidf(a[2]) * bflo(pv.y), xv.w + sigmoidf(a[3]) * bfhi(pv.y));
;       });
	v_exp_f32_e32 v29, v29
	s_waitcnt vmcnt(4)
	v_pk_fma_f32 v[42:43], v[48:49], v[50:51], v[156:157]
	v_add_f32_e32 v29, 1.0, v29
	v_rcp_f32_e32 v53, v29
	v_mul_f32_e32 v29, 0xbfb8aa3b, v40
	v_exp_f32_e32 v29, v29
	v_pk_fma_f32 v[44:45], v[52:53], v[46:47], v[158:159]
	global_store_dwordx4 v[54:55], v[42:45], off offset:128
	v_add_f32_e32 v29, 1.0, v29

; DI float bflo(unsigned u) { return __uint_as_float(u << 16); }
; DI float bfhi(unsigned u) { return __uint_as_float(u & 0xffff0000u); }
; DI float sigmoidf(float x) { return __builtin_amdgcn_rcpf(1.f + __expf(-x)); }
; __global__ void __launch_bounds__(512, 2) mega(Params p) {
;     ...
;       gemm8_epi(acc8, m0, n0, [&](int m, int n, f32x4& a) {
;         uint2 pv = *(const uint2*)(ppb + (size_t)m * DM + n);
;         float4* o = (float4*)(p.out + (size_t)m * DM + n);
;         float4 xv = *o;
;         *o = make_float4(xv.x + sigmoidf(a[0]) * bflo(pv.x), xv.y + sigmoidf(a[1]) * bfhi(pv.x),
;                          xv.z + sigmoidf(a[2]) * bflo(pv.y), xv.w + sigmoidf(a[3]) * bfhi(pv.y));
;       });
	v_rcp_f32_e32 v44, v29
	v_mul_f32_e32 v29, 0xbfb8aa3b, v41
	v_exp_f32_e32 v29, v29
	s_waitcnt vmcnt(4)
	v_lshlrev_b32_e32 v46, 16, v150
	v_add_f32_e32 v29, 1.0, v29
	v_rcp_f32_e32 v45, v29
	v_mul_f32_e32 v29, 0xbfb8aa3b, v38
	v_exp_f32_e32 v29, v29
	v_and_b32_e32 v47, 0xffff0000, v150
	v_lshlrev_b32_e32 v42, 16, v151
	v_and_b32_e32 v43, 0xffff0000, v151
	v_add_f32_e32 v29, 1.0, v29
	v_rcp_f32_e32 v48, v29
	v_mul_f32_e32 v29, 0xbfb8aa3b, v39

; DI float bflo(unsigned u) { return __uint_as_float(u << 16); }
; DI float bfhi(unsigned u) { return __uint_as_float(u & 0xffff0000u); }
; DI float sigmoidf(float x) { return __builtin_amdgcn_rcpf(1.f + __expf(-x)); }
; template <class E>
; DI void gemm8_epi(f32x4 (&acc)[8][4], int m0, int n0, E e) {
;     ...
; #pragma unroll
;   for (int i = 0; i < 8; ++i)
; #pragma unroll
;     for (int j = 0; j < 4; ++j) {
;       const int m = m0 + wm * 128 + i * 16 + (lane & 15);
;       const int n = n0 + wn * 64 + j * 16 + (lane >> 4) * 4;
;       e(m, n, acc[i][j]);
;     }
; __global__ void __launch_bounds__(512, 2) mega(Params p) {
;     ...
;       gemm8_epi(acc8, m0, n0, [&](int m, int n, f32x4& a) {
;         uint2 pv = *(const uint2*)(ppb + (size_t)m * DM + n);
;         float4* o = (float4*)(p.out + (size_t)m * DM + n);
;         float4 xv = *o;
;         *o = make_float4(xv.x + sigmoidf(a[0]) * bflo(pv.x), xv.y + sigmoidf(a[1]) * bfhi(pv.x),
;                          xv.z + sigmoidf(a[2]) * bflo(pv.y), xv.w + sigmoidf(a[3]) * bfhi(pv.y));
;       });
	v_exp_f32_e32 v29, v29
	s_waitcnt vmcnt(3)
	v_pk_fma_f32 v[38:39], v[44:45], v[46:47], v[188:189]
	v_add_f32_e32 v29, 1.0, v29
	v_rcp_f32_e32 v49, v29
	v_mul_f32_e32 v29, 0xbfb8aa3b, v36
	v_exp_f32_e32 v29, v29
	v_pk_fma_f32 v[40:41], v[48:49], v[42:43], v[190:191]
	global_store_dwordx4 v[54:55], v[38:41], off offset:192
	v_add_f32_e32 v29, 1.0, v29
	v_rcp_f32_e32 v44, v29
	v_mul_f32_e32 v29, 0xbfb8aa3b, v37
	v_exp_f32_e32 v29, v29
	v_or_b32_e32 v38, 0x60, v28
	v_ashrrev_i32_e32 v39, 31, v38
	v_lshlrev_b64 v[40:41], 11, v[38:39]
	v_add_f32_e32 v29, 1.0, v29
	v_rcp_f32_e32 v45, v29
	v_mul_f32_e32 v29, 0xbfb8aa3b, v34
	v_exp_f32_e32 v29, v29
	v_lshl_add_u64 v[40:41], s[12:13], 0, v[40:41]
	v_lshlrev_b64 v[38:39], 12, v[38:39]
	v_lshl_add_u64 v[40:41], v[40:41], 0, v[0:1]
	v_lshl_add_u64 v[38:39], s[2:3], 0, v[38:39]
	global_load_dwordx2 v[42:43], v[40:41], off
	v_lshl_add_u64 v[38:39], v[38:39], 0, v[22:23]
	v_add_f32_e32 v29, 1.0, v29
	v_rcp_f32_e32 v48, v29
	v_mul_f32_e32 v29, 0xbfb8aa3b, v35
	global_load_dwordx4 v[34:37], v[38:39], off
	global_load_dwordx2 v[146:147], v[40:41], off offset:32
	global_load_dwordx4 v[152:155], v[38:39], off offset:64
	global_load_dwordx2 v[148:149], v[40:41], off offset:64
	global_load_dwordx4 v[156:159], v[38:39], off offset:128
	global_load_dwordx2 v[150:151], v[40:41], off offset:96
	global_load_dwordx4 v[188:191], v[38:39], off offset:192
	v_exp_f32_e32 v29, v29
	s_waitcnt vmcnt(7)
	v_lshlrev_b32_e32 v46, 16, v42
	v_add_f32_e32 v29, 1.0, v29
	v_rcp_f32_e32 v49, v29
	v_and_b32_e32 v47, 0xffff0000, v42
	v_lshlrev_b32_e32 v42, 16, v43
	v_and_b32_e32 v43, 0xffff0000, v43
	s_waitcnt vmcnt(6)
	v_pk_fma_f32 v[34:35], v[44:45], v[46:47], v[34:35]
	v_pk_fma_f32 v[36:37], v[48:49], v[42:43], v[36:37]
	global_store_dwordx4 v[38:39], v[34:37], off

; DI float bflo(unsigned u) { return __uint_as_float(u << 16); }
; DI float bfhi(unsigned u) { return __uint_as_float(u & 0xffff0000u); }
; DI float sigmoidf(float x) { return __builtin_amdgcn_rcpf(1.f + __expf(-x)); }
; __global__ void __launch_bounds__(512, 2) mega(Params p) {
;     ...
;       gemm8_epi(acc8, m0, n0, [&](int m, int n, f32x4& a) {
;         uint2 pv = *(const uint2*)(ppb + (size_t)m * DM + n);
;         float4* o = (float4*)(p.out + (size_t)m * DM + n);
;         float4 xv = *o;
;         *o = make_float4(xv.x + sigmoidf(a[0]) * bflo(pv.x), xv.y + sigmoidf(a[1]) * bfhi(pv.x),
;                          xv.z + sigmoidf(a[2]) * bflo(pv.y), xv.w + sigmoidf(a[3]) * bfhi(pv.y));
;       });
	v_mul_f32_e32 v29, 0xbfb8aa3b, v32

; DI float bflo(unsigned u) { return __uint_as_float(u << 16); }
; DI float bfhi(unsigned u) { return __uint_as_float(u & 0xffff0000u); }
; DI float sigmoidf(float x) { return __builtin_amdgcn_rcpf(1.f + __expf(-x)); }
; __global__ void __launch_bounds__(512, 2) mega(Params p) {
;     ...
;       gemm8_epi(acc8, m0, n0, [&](int m, int n, f32x4& a) {
;         uint2 pv = *(const uint2*)(ppb + (size_t)m * DM + n);
;         float4* o = (float4*)(p.out + (size_t)m * DM + n);
;         float4 xv = *o;
;         *o = make_float4(xv.x + sigmoidf(a[0]) * bflo(pv.x), xv.y + sigmoidf(a[1]) * bfhi(pv.x),
;                          xv.z + sigmoidf(a[2]) * bflo(pv.y), xv.w + sigmoidf(a[3]) * bfhi(pv.y));
;       });
	v_exp_f32_e32 v29, v29
	s_waitcnt vmcnt(6)
	v_lshlrev_b32_e32 v34, 16, v146
	v_add_f32_e32 v29, 1.0, v29
	v_rcp_f32_e32 v32, v29
	v_mul_f32_e32 v29, 0xbfb8aa3b, v33
	v_exp_f32_e32 v29, v29
	v_and_b32_e32 v35, 0xffff0000, v146
	v_lshlrev_b32_e32 v36, 16, v147
	v_and_b32_e32 v37, 0xffff0000, v147
	v_add_f32_e32 v29, 1.0, v29
	v_rcp_f32_e32 v33, v29
	v_mul_f32_e32 v29, 0xbfb8aa3b, v30
	v_exp_f32_e32 v29, v29
	s_waitcnt vmcnt(5)
	v_pk_fma_f32 v[32:33], v[32:33], v[34:35], v[152:153]
	v_add_f32_e32 v29, 1.0, v29
	v_rcp_f32_e32 v30, v29
	v_mul_f32_e32 v29, 0xbfb8aa3b, v31
	v_exp_f32_e32 v29, v29
	s_nop 0
	v_add_f32_e32 v29, 1.0, v29
	v_rcp_f32_e32 v31, v29
	s_nop 0
	v_pk_fma_f32 v[34:35], v[30:31], v[36:37], v[154:155]
	global_store_dwordx4 v[38:39], v[32:35], off offset:64
	v_rcp_f32_e32 v36, v24
	v_mul_f32_e32 v24, 0xbfb8aa3b, v25
	v_rcp_f32_e32 v32, v26
	v_mul_f32_e32 v26, 0xbfb8aa3b, v27
	v_exp_f32_e32 v26, v26
	v_exp_f32_e32 v24, v24

; DI float bflo(unsigned u) { return __uint_as_float(u << 16); }
; DI float bfhi(unsigned u) { return __uint_as_float(u & 0xffff0000u); }
; DI float sigmoidf(float x) { return __builtin_amdgcn_rcpf(1.f + __expf(-x)); }
; __global__ void __launch_bounds__(512, 2) mega(Params p) {
;     ...
;       gemm8_epi(acc8, m0, n0, [&](int m, int n, f32x4& a) {
;         uint2 pv = *(const uint2*)(ppb + (size_t)m * DM + n);
;         float4* o = (float4*)(p.out + (size_t)m * DM + n);
;         float4 xv = *o;
;         *o = make_float4(xv.x + sigmoidf(a[0]) * bflo(pv.x), xv.y + sigmoidf(a[1]) * bfhi(pv.x),
;                          xv.z + sigmoidf(a[2]) * bflo(pv.y), xv.w + sigmoidf(a[3]) * bfhi(pv.y));
;       });
	v_add_f32_e32 v26, 1.0, v26
	v_add_f32_e32 v24, 1.0, v24
	v_rcp_f32_e32 v33, v26
	v_rcp_f32_e32 v37, v24

; DI float bflo(unsigned u) { return __uint_as_float(u << 16); }
; DI float bfhi(unsigned u) { return __uint_as_float(u & 0xffff0000u); }
; DI float sigmoidf(float x) { return __builtin_amdgcn_rcpf(1.f + __expf(-x)); }
; __global__ void __launch_bounds__(512, 2) mega(Params p) {
;     ...
;       gemm8_epi(acc8, m0, n0, [&](int m, int n, f32x4& a) {
;         uint2 pv = *(const uint2*)(ppb + (size_t)m * DM + n);
;         float4* o = (float4*)(p.out + (size_t)m * DM + n);
;         float4 xv = *o;
;         *o = make_float4(xv.x + sigmoidf(a[0]) * bflo(pv.x), xv.y + sigmoidf(a[1]) * bfhi(pv.x),
;                          xv.z + sigmoidf(a[2]) * bflo(pv.y), xv.w + sigmoidf(a[3]) * bfhi(pv.y));
;       });
	s_waitcnt vmcnt(5)
	v_lshlrev_b32_e32 v34, 16, v148
	v_and_b32_e32 v35, 0xffff0000, v148
	v_lshlrev_b32_e32 v30, 16, v149
	v_and_b32_e32 v31, 0xffff0000, v149
	s_waitcnt vmcnt(4)
	v_pk_fma_f32 v[24:25], v[32:33], v[34:35], v[156:157]
	v_pk_fma_f32 v[26:27], v[36:37], v[30:31], v[158:159]
	global_store_dwordx4 v[38:39], v[24:27], off offset:128

; DI float bflo(unsigned u) { return __uint_as_float(u << 16); }
; DI float bfhi(unsigned u) { return __uint_as_float(u & 0xffff0000u); }
; DI float sigmoidf(float x) { return __builtin_amdgcn_rcpf(1.f + __expf(-x)); }
; __global__ void __launch_bounds__(512, 2) mega(Params p) {
;     ...
;       gemm8_epi(acc8, m0, n0, [&](int m, int n, f32x4& a) {
;         uint2 pv = *(const uint2*)(ppb + (size_t)m * DM + n);
;         float4* o = (float4*)(p.out + (size_t)m * DM + n);
;         float4 xv = *o;
;         *o = make_float4(xv.x + sigmoidf(a[0]) * bflo(pv.x), xv.y + sigmoidf(a[1]) * bfhi(pv.x),
;                          xv.z + sigmoidf(a[2]) * bflo(pv.y), xv.w + sigmoidf(a[3]) * bfhi(pv.y));
;       });
	s_waitcnt vmcnt(4)
	v_lshlrev_b32_e32 v30, 16, v150
	v_rcp_f32_e32 v26, v18
	v_mul_f32_e32 v18, 0xbfb8aa3b, v19
	v_exp_f32_e32 v18, v18
	v_and_b32_e32 v31, 0xffff0000, v150
	v_lshlrev_b32_e32 v24, 16, v151
	v_and_b32_e32 v25, 0xffff0000, v151
	v_add_f32_e32 v18, 1.0, v18
	v_rcp_f32_e32 v27, v18
	v_mul_f32_e32 v18, 0xbfb8aa3b, v20
	v_exp_f32_e32 v18, v18
	s_nop 0
	v_add_f32_e32 v18, 1.0, v18
	v_rcp_f32_e32 v32, v18
	v_mul_f32_e32 v18, 0xbfb8aa3b, v21
	v_exp_f32_e32 v18, v18
	s_nop 0
	v_add_f32_e32 v18, 1.0, v18
	v_rcp_f32_e32 v33, v18

; DI float bflo(unsigned u) { return __uint_as_float(u << 16); }
; DI float bfhi(unsigned u) { return __uint_as_float(u & 0xffff0000u); }
; DI float sigmoidf(float x) { return __builtin_amdgcn_rcpf(1.f + __expf(-x)); }
; __global__ void __launch_bounds__(512, 2) mega(Params p) {
;     ...
;       gemm8_epi(acc8, m0, n0, [&](int m, int n, f32x4& a) {
;         uint2 pv = *(const uint2*)(ppb + (size_t)m * DM + n);
;         float4* o = (float4*)(p.out + (size_t)m * DM + n);
;         float4 xv = *o;
;         *o = make_float4(xv.x + sigmoidf(a[0]) * bflo(pv.x), xv.y + sigmoidf(a[1]) * bfhi(pv.x),
;                          xv.z + sigmoidf(a[2]) * bflo(pv.y), xv.w + sigmoidf(a[3]) * bfhi(pv.y));
;       });
	s_waitcnt vmcnt(3)
	v_pk_fma_f32 v[18:19], v[26:27], v[30:31], v[188:189]
	v_pk_fma_f32 v[20:21], v[32:33], v[24:25], v[190:191]
	global_store_dwordx4 v[38:39], v[18:21], off offset:192
	s_nop 1
	v_or_b32_e32 v18, 0x70, v28
	v_ashrrev_i32_e32 v19, 31, v18
	v_lshlrev_b64 v[20:21], 11, v[18:19]
	v_lshl_add_u64 v[20:21], s[12:13], 0, v[20:21]
	v_lshl_add_u64 v[20:21], v[20:21], 0, v[0:1]
	v_mul_f32_e32 v0, 0xbfb8aa3b, v14
	v_exp_f32_e32 v0, v0
	v_lshlrev_b64 v[18:19], 12, v[18:19]
	v_lshl_add_u64 v[18:19], s[2:3], 0, v[18:19]
	v_lshl_add_u64 v[18:19], v[18:19], 0, v[22:23]
	v_add_f32_e32 v0, 1.0, v0
	v_rcp_f32_e32 v22, v0
	v_mul_f32_e32 v0, 0xbfb8aa3b, v15
	v_exp_f32_e32 v0, v0
	global_load_dwordx2 v[24:25], v[20:21], off
	v_add_f32_e32 v0, 1.0, v0
	v_rcp_f32_e32 v23, v0
	v_mul_f32_e32 v0, 0xbfb8aa3b, v16
	v_exp_f32_e32 v0, v0
	s_waitcnt vmcnt(0)
	v_lshlrev_b32_e32 v26, 16, v24
	v_add_f32_e32 v0, 1.0, v0
	v_rcp_f32_e32 v28, v0
	v_mul_f32_e32 v0, 0xbfb8aa3b, v17
	global_load_dwordx4 v[14:17], v[18:19], off
	global_load_dwordx2 v[146:147], v[20:21], off offset:32
	global_load_dwordx4 v[152:155], v[18:19], off offset:64
	global_load_dwordx2 v[148:149], v[20:21], off offset:64
	global_load_dwordx4 v[156:159], v[18:19], off offset:128
	global_load_dwordx2 v[150:151], v[20:21], off offset:96
	global_load_dwordx4 v[188:191], v[18:19], off offset:192
	v_exp_f32_e32 v0, v0
	v_and_b32_e32 v27, 0xffff0000, v24
	v_lshlrev_b32_e32 v24, 16, v25
	v_and_b32_e32 v25, 0xffff0000, v25
	v_add_f32_e32 v0, 1.0, v0
	v_rcp_f32_e32 v29, v0
	v_mul_f32_e32 v0, 0xbfb8aa3b, v10
	v_exp_f32_e32 v0, v0
	s_waitcnt vmcnt(6)
	v_pk_fma_f32 v[14:15], v[22:23], v[26:27], v[14:15]
	v_pk_fma_f32 v[16:17], v[28:29], v[24:25], v[16:17]
	global_store_dwordx4 v[18:19], v[14:17], off

; DI float bflo(unsigned u) { return __uint_as_float(u << 16); }
; DI float bfhi(unsigned u) { return __uint_as_float(u & 0xffff0000u); }
; DI float sigmoidf(float x) { return __builtin_amdgcn_rcpf(1.f + __expf(-x)); }
; __global__ void __launch_bounds__(512, 2) mega(Params p) {
;     ...
;       gemm8_epi(acc8, m0, n0, [&](int m, int n, f32x4& a) {
;         uint2 pv = *(const uint2*)(ppb + (size_t)m * DM + n);
;         float4* o = (float4*)(p.out + (size_t)m * DM + n);
;         float4 xv = *o;
;         *o = make_float4(xv.x + sigmoidf(a[0]) * bflo(pv.x), xv.y + sigmoidf(a[1]) * bfhi(pv.x),
;                          xv.z + sigmoidf(a[2]) * bflo(pv.y), xv.w + sigmoidf(a[3]) * bfhi(pv.y));
;       });
	v_add_f32_e32 v0, 1.0, v0

; DI float bflo(unsigned u) { return __uint_as_float(u << 16); }
; DI float bfhi(unsigned u) { return __uint_as_float(u & 0xffff0000u); }
; DI float sigmoidf(float x) { return __builtin_amdgcn_rcpf(1.f + __expf(-x)); }
; __global__ void __launch_bounds__(512, 2) mega(Params p) {
;     ...
;       gemm8_epi(acc8, m0, n0, [&](int m, int n, f32x4& a) {
;         uint2 pv = *(const uint2*)(ppb + (size_t)m * DM + n);
;         float4* o = (float4*)(p.out + (size_t)m * DM + n);
;         float4 xv = *o;
;         *o = make_float4(xv.x + sigmoidf(a[0]) * bflo(pv.x), xv.y + sigmoidf(a[1]) * bfhi(pv.x),
;                          xv.z + sigmoidf(a[2]) * bflo(pv.y), xv.w + sigmoidf(a[3]) * bfhi(pv.y));
;       });
	v_rcp_f32_e32 v10, v0
	v_mul_f32_e32 v0, 0xbfb8aa3b, v11
	v_exp_f32_e32 v0, v0
	s_waitcnt vmcnt(6)
	v_lshlrev_b32_e32 v14, 16, v146
	v_add_f32_e32 v0, 1.0, v0
	v_rcp_f32_e32 v11, v0
	v_mul_f32_e32 v0, 0xbfb8aa3b, v12
	v_exp_f32_e32 v0, v0
	v_and_b32_e32 v15, 0xffff0000, v146
	v_lshlrev_b32_e32 v16, 16, v147
	v_and_b32_e32 v17, 0xffff0000, v147
	v_add_f32_e32 v0, 1.0, v0
	v_rcp_f32_e32 v12, v0
	v_mul_f32_e32 v0, 0xbfb8aa3b, v13
	v_exp_f32_e32 v0, v0
	s_waitcnt vmcnt(5)
	v_pk_fma_f32 v[10:11], v[10:11], v[14:15], v[152:153]
	v_add_f32_e32 v0, 1.0, v0
	v_rcp_f32_e32 v13, v0
	v_mul_f32_e32 v0, 0xbfb8aa3b, v6
	v_exp_f32_e32 v0, v0
	v_pk_fma_f32 v[12:13], v[12:13], v[16:17], v[154:155]
	global_store_dwordx4 v[18:19], v[10:13], off offset:64
	v_add_f32_e32 v0, 1.0, v0

; DI float bflo(unsigned u) { return __uint_as_float(u << 16); }
; DI float bfhi(unsigned u) { return __uint_as_float(u & 0xffff0000u); }
; DI float sigmoidf(float x) { return __builtin_amdgcn_rcpf(1.f + __expf(-x)); }
; __global__ void __launch_bounds__(512, 2) mega(Params p) {
;     ...
;       gemm8_epi(acc8, m0, n0, [&](int m, int n, f32x4& a) {
;         uint2 pv = *(const uint2*)(ppb + (size_t)m * DM + n);
;         float4* o = (float4*)(p.out + (size_t)m * DM + n);
;         float4 xv = *o;
;         *o = make_float4(xv.x + sigmoidf(a[0]) * bflo(pv.x), xv.y + sigmoidf(a[1]) * bfhi(pv.x),
;                          xv.z + sigmoidf(a[2]) * bflo(pv.y), xv.w + sigmoidf(a[3]) * bfhi(pv.y));
;       });
	v_rcp_f32_e32 v12, v0
	v_mul_f32_e32 v0, 0xbfb8aa3b, v7
	v_exp_f32_e32 v0, v0
	s_waitcnt vmcnt(5)
	v_lshlrev_b32_e32 v14, 16, v148
	v_add_f32_e32 v0, 1.0, v0
	v_rcp_f32_e32 v13, v0
	v_mul_f32_e32 v0, 0xbfb8aa3b, v8
	v_exp_f32_e32 v0, v0
	v_and_b32_e32 v15, 0xffff0000, v148
	v_lshlrev_b32_e32 v10, 16, v149
	v_and_b32_e32 v11, 0xffff0000, v149
	v_add_f32_e32 v0, 1.0, v0
	v_rcp_f32_e32 v16, v0
	v_mul_f32_e32 v0, 0xbfb8aa3b, v9

; DI float bflo(unsigned u) { return __uint_as_float(u << 16); }
; DI float bfhi(unsigned u) { return __uint_as_float(u & 0xffff0000u); }
; DI float sigmoidf(float x) { return __builtin_amdgcn_rcpf(1.f + __expf(-x)); }
; __global__ void __launch_bounds__(512, 2) mega(Params p) {
;     ...
;       gemm8_epi(acc8, m0, n0, [&](int m, int n, f32x4& a) {
;         uint2 pv = *(const uint2*)(ppb + (size_t)m * DM + n);
;         float4* o = (float4*)(p.out + (size_t)m * DM + n);
;         float4 xv = *o;
;         *o = make_float4(xv.x + sigmoidf(a[0]) * bflo(pv.x), xv.y + sigmoidf(a[1]) * bfhi(pv.x),
;                          xv.z + sigmoidf(a[2]) * bflo(pv.y), xv.w + sigmoidf(a[3]) * bfhi(pv.y));
;       });
	v_exp_f32_e32 v0, v0
	s_waitcnt vmcnt(4)
	v_pk_fma_f32 v[6:7], v[12:13], v[14:15], v[156:157]
	v_add_f32_e32 v0, 1.0, v0
	v_rcp_f32_e32 v17, v0
	v_mul_f32_e32 v0, 0xbfb8aa3b, v2
	v_exp_f32_e32 v0, v0
	v_pk_fma_f32 v[8:9], v[16:17], v[10:11], v[158:159]
	global_store_dwordx4 v[18:19], v[6:9], off offset:128
	v_add_f32_e32 v0, 1.0, v0

; DI float bflo(unsigned u) { return __uint_as_float(u << 16); }
; DI float bfhi(unsigned u) { return __uint_as_float(u & 0xffff0000u); }
; DI float sigmoidf(float x) { return __builtin_amdgcn_rcpf(1.f + __expf(-x)); }
; __global__ void __launch_bounds__(512, 2) mega(Params p) {
;     ...
;       gemm8_epi(acc8, m0, n0, [&](int m, int n, f32x4& a) {
;         uint2 pv = *(const uint2*)(ppb + (size_t)m * DM + n);
;         float4* o = (float4*)(p.out + (size_t)m * DM + n);
;         float4 xv = *o;
;         *o = make_float4(xv.x + sigmoidf(a[0]) * bflo(pv.x), xv.y + sigmoidf(a[1]) * bfhi(pv.x),
;                          xv.z + sigmoidf(a[2]) * bflo(pv.y), xv.w + sigmoidf(a[3]) * bfhi(pv.y));
;       });
	v_rcp_f32_e32 v8, v0
	v_mul_f32_e32 v0, 0xbfb8aa3b, v3
	v_exp_f32_e32 v0, v0
	s_waitcnt vmcnt(4)
	v_lshlrev_b32_e32 v10, 16, v150
	v_add_f32_e32 v0, 1.0, v0
	v_rcp_f32_e32 v9, v0
	v_mul_f32_e32 v0, 0xbfb8aa3b, v4
	v_exp_f32_e32 v0, v0
	v_and_b32_e32 v11, 0xffff0000, v150
	v_lshlrev_b32_e32 v6, 16, v151
	v_and_b32_e32 v7, 0xffff0000, v151
	v_add_f32_e32 v0, 1.0, v0
	v_rcp_f32_e32 v12, v0
	v_mul_f32_e32 v0, 0xbfb8aa3b, v5

; DI float bflo(unsigned u) { return __uint_as_float(u << 16); }
; DI float bfhi(unsigned u) { return __uint_as_float(u & 0xffff0000u); }
; DI float sigmoidf(float x) { return __builtin_amdgcn_rcpf(1.f + __expf(-x)); }
; __global__ void __launch_bounds__(512, 2) mega(Params p) {
;     ...
;       gemm8_epi(acc8, m0, n0, [&](int m, int n, f32x4& a) {
;         uint2 pv = *(const uint2*)(ppb + (size_t)m * DM + n);
;         float4* o = (float4*)(p.out + (size_t)m * DM + n);
;         float4 xv = *o;
;         *o = make_float4(xv.x + sigmoidf(a[0]) * bflo(pv.x), xv.y + sigmoidf(a[1]) * bfhi(pv.x),
;                          xv.z + sigmoidf(a[2]) * bflo(pv.y), xv.w + sigmoidf(a[3]) * bfhi(pv.y));
;       });
	v_exp_f32_e32 v0, v0
	s_waitcnt vmcnt(3)
	v_pk_fma_f32 v[2:3], v[8:9], v[10:11], v[188:189]
	v_add_f32_e32 v0, 1.0, v0
	v_rcp_f32_e32 v13, v0
	s_nop 0
	v_pk_fma_f32 v[4:5], v[12:13], v[6:7], v[190:191]
	global_store_dwordx4 v[18:19], v[2:5], off offset:192
	s_cbranch_vccnz .LBB0_998
